# u5 plus Mamba y dot-product folded into one accumulation chain (one packed add fewer per step)
# baseline (speedup 1.0000x reference)
; DI float row16_sum(float v) { v += dppf(v, 0); v += dppf(v, 1); v += dppf(v, 2); v += dppf(v, 3); return v; }
; DI void mamba_scan(CP p, const Ptrs& w, int l, int item, float* sm) {
;     ...
;   auto load = [&](int c, MPre& P) {
; #pragma unroll
;     for (int i = 0; i < 2; ++i) {
;       int idx = tid + 256 * i, j = idx >> 5, q = idx & 31;
;       int ii = pos2i(c * 16 + j, dir);
;       P.pbq[i] = *(const uint4*)(mbc + ((size_t)b * TPB + ii) * 512 + (q < 16 ? 0 : 256) + gp * 128 + (q & 15) * 8);
;     }
;     {
;       int pos = c * 16 + xj, ii = pos2i(pos, dir);
;       size_t tok = (size_t)b * TPB + ii;
;       const bf16_t* prw = w.pC + tok * SPC;
;       bool hp = (ii != 0) && (ii != CTXL), hn = (ii != CTXL - 1) && (ii != TPB - 1);
;       P.px[0] = prw[chX + (hp ? -SPC : 0)]; P.px[1] = prw[chX]; P.px[2] = prw[chX + (hn ? SPC : 0)];
;       P.pxm[0] = hp ? 1.f : 0.f; P.pxm[1] = hn ? 1.f : 0.f;
;       float2 dd = *(const float2*)(w.mdt + (tok * 16 + dir * 8 + hd) * 2);
;       P.pdt[0] = dd.x; P.pdt[1] = dd.y; P.pdt[2] = w.mcb[tok * 2 + gp];
;     }
;     ...
;   auto flush = [&](int c) {
;     {
;       int j = tid >> 4, rr = tid & 15;
;       int ii = pos2i(c * 16 + j, dir);
;       yout[((size_t)b * TPB + ii) * 512 + hd * 64 + pq * 16 + rr] = f2bf(sY[(c & 1) * 256 + j * 16 + rr]);
;     }
;   };
;   __syncthreads();
;   load(0, PA);
;   stage(PA, sm);
;   load(1, PB);
;   __syncthreads();
;   const int NCH = TPB / 16;
;   auto run_chunk = [&](int c, const float* bf, float* sy) {
;     flush(max(c - 1, 0));
;     MStep cur = lds_step(bf, 0);
; #pragma unroll
;     for (int j = 0; j < 16; ++j) {
;       MStep nxt = cur;
;       if (j + 1 < 16) nxt = lds_step(bf, j + 1);
;       f2v ya = M0 * cur.C0.xy + M1 * cur.C0.zw, yb = M2 * cur.C1.xy + M3 * cur.C1.zw;
;       ya += yb;
;       float yp = row16_sum(ya.x + ya.y);
;       float y = cur.sc.x * yp + cur.xq * cur.sc.y + cur.ds;
;       const float dA = cur.sc.x, xq = cur.xq;
;       M0 = M0 * dA + xq * cur.B0.xy; M1 = M1 * dA + xq * cur.B0.zw;
;       M2 = M2 * dA + xq * cur.B1.xy; M3 = M3 * dA + xq * cur.B1.zw;
;       sy[(ng == 0 ? j * 16 : 0) + ysel] = y;
;       cur = nxt;
.LBB0_544:
	s_min_u32 s4, s52, 1
	s_lshl_b32 s5, s4, 8
	s_lshl_b32 s54, s4, 4
	s_add_i32 s4, s7, 4
	s_min_u32 s4, s4, 0x20f
	s_lshl_b32 s42, s4, 4
	v_add_u32_e32 v8, s42, v55
	s_sub_i32 s53, s57, s5
	v_cmp_lt_i32_e64 s[4:5], s37, v8
	v_mov_b64_e32 v[38:39], s[48:49]
	v_mov_b32_e32 v41, v157
	v_cndmask_b32_e64 v12, v231, v232, s[4:5]
	v_sub_u32_e32 v12, v12, v8
	v_cndmask_b32_e64 v12, v12, v8, s[40:41]
	v_add_u32_e32 v8, s42, v56
	v_cmp_lt_i32_e64 s[4:5], s37, v8
	v_ashrrev_i32_e32 v13, 31, v12
	v_lshl_add_u64 v[12:13], v[12:13], 0, s[90:91]
	v_cndmask_b32_e64 v14, v231, v232, s[4:5]
	v_sub_u32_e32 v14, v14, v8
	v_cndmask_b32_e64 v14, v14, v8, s[40:41]
	v_add_u32_e32 v8, s42, v54
	v_cmp_lt_i32_e64 s[4:5], s37, v8
	v_ashrrev_i32_e32 v15, 31, v14
	v_lshl_add_u64 v[14:15], v[14:15], 0, s[90:91]
	v_cndmask_b32_e64 v16, v231, v232, s[4:5]
	v_sub_u32_e32 v16, v16, v8
	v_cndmask_b32_e64 v16, v16, v8, s[40:41]
	v_and_b32_e32 v8, 0xfffffeff, v16
	v_ashrrev_i32_e32 v17, 31, v16
	v_cmp_eq_u32_e64 s[42:43], 0, v8
	v_lshl_add_u64 v[36:37], v[16:17], 0, s[90:91]
	v_mad_u64_u32 v[38:39], s[4:5], v36, s92, v[38:39]
	v_cndmask_b32_e64 v8, v233, 0, s[42:43]
	v_and_b32_e32 v40, 0xffffdfff, v16
	v_add_u32_e32 v16, v8, v48
	v_lshlrev_b64 v[12:13], 10, v[12:13]
	v_lshlrev_b64 v[14:15], 10, v[14:15]
	v_mad_i32_i24 v39, v37, s92, v39
	v_ashrrev_i32_e32 v17, 31, v16
	v_cmp_eq_u32_e64 s[44:45], s37, v40
	v_lshlrev_b64 v[42:43], 7, v[36:37]
	v_lshl_add_u64 v[12:13], v[30:31], 0, v[12:13]
	v_lshl_add_u64 v[14:15], v[30:31], 0, v[14:15]
	v_lshl_add_u64 v[16:17], v[16:17], 1, v[38:39]
	v_lshl_add_u64 v[38:39], v[38:39], 0, v[156:157]
	v_cndmask_b32_e64 v40, v234, 0, s[44:45]
	v_lshl_or_b32 v42, s6, 3, v42
	global_load_dwordx4 v[18:21], v[12:13], off
	s_nop 0
	global_load_dwordx4 v[12:15], v[14:15], off
	v_lshl_add_u64 v[40:41], v[38:39], 0, v[40:41]
	v_lshl_add_u64 v[42:43], s[46:47], 0, v[42:43]
	v_lshl_add_u64 v[44:45], v[36:37], 3, s[50:51]
	global_load_ushort v84, v[16:17], off
	global_load_ushort v85, v[38:39], off
	global_load_ushort v83, v[40:41], off
	global_load_dwordx2 v[36:37], v[42:43], off
	s_nop 0
	global_load_dword v17, v[44:45], off
	v_subrev_u32_e32 v8, s54, v82
	s_and_b32 s4, s53, 0x100
	v_lshl_add_u32 v16, s4, 2, v57
	v_cmp_lt_i32_e64 s[4:5], s37, v8
	ds_read_b32 v16, v16 offset:37376
	s_nop 0
	v_cndmask_b32_e64 v38, v231, v232, s[4:5]
	v_add3_u32 v38, v38, v81, s54
	v_cndmask_b32_e64 v38, v38, v8, s[40:41]
	v_ashrrev_i32_e32 v39, 31, v38
	v_lshl_add_u64 v[38:39], v[38:39], 0, s[90:91]
	v_lshlrev_b64 v[38:39], 10, v[38:39]
	s_waitcnt lgkmcnt(0)
	v_cvt_pk_bf16_f32 v8, v16, s0
	v_lshl_add_u64 v[38:39], v[34:35], 0, v[38:39]
	global_store_short v[38:39], v8, off
	s_waitcnt lgkmcnt(0)
	ds_read_b128 v[38:41], v59
	ds_read_b128 v[42:45], v59 offset:16
	ds_read_b128 v[88:91], v59 offset:8192
	ds_read_b128 v[92:95], v59 offset:8208
	v_add_u32_e32 v8, 0x4000, v60
	s_movk_i32 s4, 0x4800
	ds_read2_b32 v[46:47], v8 offset1:16
	v_add_u32_e32 v8, 0x4400, v60
	ds_read2_b32 v[116:117], v8 offset1:16
	v_add_u32_e64 v8, s4, 0
	ds_read2_b64 v[96:99], v8 offset1:2
	ds_read_b128 v[100:103], v59 offset:512
	ds_read_b128 v[104:107], v59 offset:528
	ds_read_b128 v[108:111], v59 offset:8704
	ds_read_b128 v[112:115], v59 offset:8720
	s_waitcnt lgkmcnt(7)
	v_pk_mul_f32 v[90:91], v[28:29], v[90:91]
	v_pk_fma_f32 v[88:89], v[26:27], v[88:89], v[90:91]
	v_pk_fma_f32 v[88:89], v[24:25], v[94:95], v[88:89]
	v_pk_fma_f32 v[88:89], v[22:23], v[92:93], v[88:89]
	v_add_f32_e32 v8, v88, v89
	s_waitcnt lgkmcnt(4)
	v_pk_mul_f32 v[22:23], v[22:23], v[96:97] op_sel_hi:[1,0]
	v_pk_mul_f32 v[26:27], v[26:27], v[96:97] op_sel_hi:[1,0]
	v_add_f32_dpp v8, v8, v8 quad_perm:[1,0,3,2] row_mask:0xf bank_mask:0xf bound_ctrl:1
	v_pk_fma_f32 v[92:93], v[42:43], v[46:47], v[22:23] op_sel_hi:[1,0,1]
	v_pk_mul_f32 v[22:23], v[24:25], v[96:97] op_sel_hi:[1,0]
	v_add_f32_dpp v8, v8, v8 quad_perm:[2,3,0,1] row_mask:0xf bank_mask:0xf bound_ctrl:1
	v_pk_fma_f32 v[88:89], v[38:39], v[46:47], v[26:27] op_sel_hi:[1,0,1]
	v_pk_mul_f32 v[26:27], v[28:29], v[96:97] op_sel_hi:[1,0]
	v_add_f32_dpp v8, v8, v8 row_half_mirror row_mask:0xf bank_mask:0xf bound_ctrl:1
	v_pk_fma_f32 v[94:95], v[44:45], v[46:47], v[22:23] op_sel_hi:[1,0,1]
	v_pk_fma_f32 v[90:91], v[40:41], v[46:47], v[26:27] op_sel_hi:[1,0,1]
	v_add_f32_dpp v8, v8, v8 row_mirror row_mask:0xf bank_mask:0xf bound_ctrl:1
	v_mul_f32_e32 v8, v96, v8
	v_fmac_f32_e32 v8, v46, v97
	v_add_f32_e32 v8, v116, v8
	ds_write_b32 v61, v8 offset:37376
	ds_read_b128 v[22:25], v59 offset:1024
	ds_read_b128 v[26:29], v59 offset:1040
	ds_read_b128 v[38:41], v59 offset:9216
	s_waitcnt lgkmcnt(4)
	v_pk_mul_f32 v[96:97], v[90:91], v[110:111]
	ds_read_b128 v[42:45], v59 offset:9232
	v_pk_fma_f32 v[96:97], v[88:89], v[108:109], v[96:97]
	ds_read_b32 v8, v60 offset:16512
	v_pk_fma_f32 v[96:97], v[94:95], v[114:115], v[96:97]
	ds_read_b32 v116, v60 offset:17536
	v_pk_fma_f32 v[96:97], v[92:93], v[112:113], v[96:97]
	ds_read_b64 v[118:119], v157 offset:18464
	v_add_f32_e32 v16, v96, v97
	v_pk_mul_f32 v[88:89], v[88:89], v[98:99] op_sel_hi:[1,0]
	s_nop 0
	v_add_f32_dpp v16, v16, v16 quad_perm:[1,0,3,2] row_mask:0xf bank_mask:0xf bound_ctrl:1
	s_nop 1
	v_add_f32_dpp v16, v16, v16 quad_perm:[2,3,0,1] row_mask:0xf bank_mask:0xf bound_ctrl:1
	s_nop 1
	v_add_f32_dpp v16, v16, v16 row_half_mirror row_mask:0xf bank_mask:0xf bound_ctrl:1
	s_nop 1
	v_add_f32_dpp v16, v16, v16 row_mirror row_mask:0xf bank_mask:0xf bound_ctrl:1
	v_mul_f32_e32 v16, v98, v16
	v_fmac_f32_e32 v16, v47, v99
	v_add_f32_e32 v96, v117, v16
	v_mov_b32_e32 v16, v47
	ds_write_b32 v62, v96 offset:37376
	v_pk_fma_f32 v[46:47], v[100:101], v[16:17], v[88:89] op_sel_hi:[1,0,1]
	v_pk_mul_f32 v[88:89], v[90:91], v[98:99] op_sel_hi:[1,0]
	v_pk_fma_f32 v[108:109], v[102:103], v[16:17], v[88:89] op_sel_hi:[1,0,1]
	v_pk_mul_f32 v[88:89], v[92:93], v[98:99] op_sel_hi:[1,0]
	v_pk_fma_f32 v[104:105], v[104:105], v[16:17], v[88:89] op_sel_hi:[1,0,1]
	v_pk_mul_f32 v[88:89], v[94:95], v[98:99] op_sel_hi:[1,0]
	v_pk_fma_f32 v[106:107], v[106:107], v[16:17], v[88:89] op_sel_hi:[1,0,1]
	ds_read_b128 v[88:91], v59 offset:1536
	ds_read_b128 v[92:95], v59 offset:1552
	ds_read_b128 v[96:99], v59 offset:9728
	ds_read_b128 v[100:103], v59 offset:9744
	ds_read_b32 v16, v60 offset:16576
	ds_read_b32 v114, v60 offset:17600
	s_waitcnt lgkmcnt(14)
; DI float row16_sum(float v) { v += dppf(v, 0); v += dppf(v, 1); v += dppf(v, 2); v += dppf(v, 3); return v; }
; DI void mamba_scan(CP p, const Ptrs& w, int l, int item, float* sm) {
;     ...
;     MStep cur = lds_step(bf, 0);
; #pragma unroll
;     for (int j = 0; j < 16; ++j) {
;       MStep nxt = cur;
;       if (j + 1 < 16) nxt = lds_step(bf, j + 1);
;       f2v ya = M0 * cur.C0.xy + M1 * cur.C0.zw, yb = M2 * cur.C1.xy + M3 * cur.C1.zw;
;       ya += yb;
;       float yp = row16_sum(ya.x + ya.y);
;       float y = cur.sc.x * yp + cur.xq * cur.sc.y + cur.ds;
;       const float dA = cur.sc.x, xq = cur.xq;
;       M0 = M0 * dA + xq * cur.B0.xy; M1 = M1 * dA + xq * cur.B0.zw;
;       M2 = M2 * dA + xq * cur.B1.xy; M3 = M3 * dA + xq * cur.B1.zw;
;       sy[(ng == 0 ? j * 16 : 0) + ysel] = y;
;       cur = nxt;
	ds_read_b64 v[110:111], v157 offset:18480
	s_waitcnt lgkmcnt(7)
	v_pk_mul_f32 v[40:41], v[108:109], v[40:41]
	v_pk_fma_f32 v[38:39], v[46:47], v[38:39], v[40:41]
	v_pk_fma_f32 v[38:39], v[106:107], v[44:45], v[38:39]
	v_pk_fma_f32 v[38:39], v[104:105], v[42:43], v[38:39]
	v_add_f32_e32 v38, v38, v39
	s_nop 1
	v_add_f32_dpp v38, v38, v38 quad_perm:[1,0,3,2] row_mask:0xf bank_mask:0xf bound_ctrl:1
	s_nop 1
	v_add_f32_dpp v38, v38, v38 quad_perm:[2,3,0,1] row_mask:0xf bank_mask:0xf bound_ctrl:1
	s_nop 1
	v_add_f32_dpp v38, v38, v38 row_half_mirror row_mask:0xf bank_mask:0xf bound_ctrl:1
	s_nop 1
	v_add_f32_dpp v38, v38, v38 row_mirror row_mask:0xf bank_mask:0xf bound_ctrl:1
	v_mul_f32_e32 v38, v118, v38
	v_fmac_f32_e32 v38, v8, v119
	v_add_f32_e32 v40, v116, v38
	v_pk_mul_f32 v[38:39], v[46:47], v[118:119] op_sel_hi:[1,0]
	ds_write_b32 v63, v40 offset:37376
	v_pk_fma_f32 v[46:47], v[22:23], v[8:9], v[38:39] op_sel_hi:[1,0,1]
	v_pk_mul_f32 v[22:23], v[108:109], v[118:119] op_sel_hi:[1,0]
	v_pk_fma_f32 v[108:109], v[24:25], v[8:9], v[22:23] op_sel_hi:[1,0,1]
	v_pk_mul_f32 v[22:23], v[104:105], v[118:119] op_sel_hi:[1,0]
	v_pk_fma_f32 v[104:105], v[26:27], v[8:9], v[22:23] op_sel_hi:[1,0,1]
	v_pk_mul_f32 v[22:23], v[106:107], v[118:119] op_sel_hi:[1,0]
	v_pk_fma_f32 v[106:107], v[28:29], v[8:9], v[22:23] op_sel_hi:[1,0,1]
	ds_read_b128 v[22:25], v59 offset:2048
	ds_read_b128 v[26:29], v59 offset:2064
	ds_read_b128 v[38:41], v59 offset:10240
	ds_read_b128 v[42:45], v59 offset:10256
	ds_read_b32 v8, v60 offset:16640
	ds_read_b32 v115, v60 offset:17664
	ds_read_b64 v[112:113], v157 offset:18496
	s_waitcnt lgkmcnt(7)
	v_pk_mul_f32 v[98:99], v[108:109], v[98:99]
	v_pk_fma_f32 v[96:97], v[46:47], v[96:97], v[98:99]
	v_pk_mul_f32 v[46:47], v[46:47], v[110:111] op_sel_hi:[1,0]
	v_pk_fma_f32 v[96:97], v[106:107], v[102:103], v[96:97]
	v_pk_fma_f32 v[46:47], v[88:89], v[16:17], v[46:47] op_sel_hi:[1,0,1]
	v_pk_mul_f32 v[88:89], v[108:109], v[110:111] op_sel_hi:[1,0]
	v_pk_fma_f32 v[96:97], v[104:105], v[100:101], v[96:97]
	v_pk_fma_f32 v[108:109], v[90:91], v[16:17], v[88:89] op_sel_hi:[1,0,1]
	v_pk_mul_f32 v[88:89], v[104:105], v[110:111] op_sel_hi:[1,0]
	v_add_f32_e32 v96, v96, v97
	v_pk_fma_f32 v[104:105], v[92:93], v[16:17], v[88:89] op_sel_hi:[1,0,1]
	v_pk_mul_f32 v[88:89], v[106:107], v[110:111] op_sel_hi:[1,0]
	v_add_f32_dpp v96, v96, v96 quad_perm:[1,0,3,2] row_mask:0xf bank_mask:0xf bound_ctrl:1
	v_pk_fma_f32 v[106:107], v[94:95], v[16:17], v[88:89] op_sel_hi:[1,0,1]
	s_waitcnt lgkmcnt(0)
	v_pk_mul_f32 v[40:41], v[108:109], v[40:41]
	v_add_f32_dpp v96, v96, v96 quad_perm:[2,3,0,1] row_mask:0xf bank_mask:0xf bound_ctrl:1
	v_pk_fma_f32 v[38:39], v[46:47], v[38:39], v[40:41]
	v_pk_fma_f32 v[38:39], v[106:107], v[44:45], v[38:39]
	v_add_f32_dpp v96, v96, v96 row_half_mirror row_mask:0xf bank_mask:0xf bound_ctrl:1
	v_pk_fma_f32 v[38:39], v[104:105], v[42:43], v[38:39]
	v_add_f32_e32 v38, v38, v39
	v_add_f32_dpp v96, v96, v96 row_mirror row_mask:0xf bank_mask:0xf bound_ctrl:1
	v_mul_f32_e32 v96, v110, v96
	v_add_f32_dpp v38, v38, v38 quad_perm:[1,0,3,2] row_mask:0xf bank_mask:0xf bound_ctrl:1
	v_fmac_f32_e32 v96, v16, v111
	v_add_f32_e32 v96, v114, v96
	v_add_f32_dpp v38, v38, v38 quad_perm:[2,3,0,1] row_mask:0xf bank_mask:0xf bound_ctrl:1
	ds_write_b32 v65, v96 offset:37376
	ds_read_b128 v[88:91], v59 offset:2560
	v_add_f32_dpp v38, v38, v38 row_half_mirror row_mask:0xf bank_mask:0xf bound_ctrl:1
	ds_read_b128 v[92:95], v59 offset:2576
	ds_read_b128 v[96:99], v59 offset:10752
	v_add_f32_dpp v38, v38, v38 row_mirror row_mask:0xf bank_mask:0xf bound_ctrl:1
	ds_read_b128 v[100:103], v59 offset:10768
	v_mul_f32_e32 v38, v112, v38
	ds_read_b32 v16, v60 offset:16704
	v_fmac_f32_e32 v38, v8, v113
	ds_read_b32 v114, v60 offset:17728
	v_add_f32_e32 v40, v115, v38
	v_pk_mul_f32 v[38:39], v[46:47], v[112:113] op_sel_hi:[1,0]
	ds_read_b64 v[110:111], v157 offset:18512
	v_pk_fma_f32 v[46:47], v[22:23], v[8:9], v[38:39] op_sel_hi:[1,0,1]
	v_pk_mul_f32 v[22:23], v[108:109], v[112:113] op_sel_hi:[1,0]
	ds_write_b32 v66, v40 offset:37376
	v_pk_fma_f32 v[108:109], v[24:25], v[8:9], v[22:23] op_sel_hi:[1,0,1]
	v_pk_mul_f32 v[22:23], v[104:105], v[112:113] op_sel_hi:[1,0]
	v_pk_fma_f32 v[104:105], v[26:27], v[8:9], v[22:23] op_sel_hi:[1,0,1]
	v_pk_mul_f32 v[22:23], v[106:107], v[112:113] op_sel_hi:[1,0]
	v_pk_fma_f32 v[106:107], v[28:29], v[8:9], v[22:23] op_sel_hi:[1,0,1]
	ds_read_b128 v[22:25], v59 offset:3072
	ds_read_b128 v[26:29], v59 offset:3088
	ds_read_b128 v[38:41], v59 offset:11264
	ds_read_b128 v[42:45], v59 offset:11280
	ds_read_b32 v8, v60 offset:16768
	ds_read_b32 v115, v60 offset:17792
	s_waitcnt lgkmcnt(14)
	ds_read_b64 v[112:113], v157 offset:18528
	s_waitcnt lgkmcnt(7)
	v_pk_mul_f32 v[98:99], v[108:109], v[98:99]
	v_pk_fma_f32 v[96:97], v[46:47], v[96:97], v[98:99]
	v_pk_fma_f32 v[96:97], v[106:107], v[102:103], v[96:97]
	v_pk_fma_f32 v[96:97], v[104:105], v[100:101], v[96:97]
	v_add_f32_e32 v96, v96, v97
	v_pk_mul_f32 v[46:47], v[46:47], v[110:111] op_sel_hi:[1,0]
	v_pk_fma_f32 v[46:47], v[88:89], v[16:17], v[46:47] op_sel_hi:[1,0,1]
	v_add_f32_dpp v96, v96, v96 quad_perm:[1,0,3,2] row_mask:0xf bank_mask:0xf bound_ctrl:1
	v_pk_mul_f32 v[88:89], v[108:109], v[110:111] op_sel_hi:[1,0]
	v_pk_fma_f32 v[108:109], v[90:91], v[16:17], v[88:89] op_sel_hi:[1,0,1]
	v_pk_mul_f32 v[88:89], v[104:105], v[110:111] op_sel_hi:[1,0]
	v_add_f32_dpp v96, v96, v96 quad_perm:[2,3,0,1] row_mask:0xf bank_mask:0xf bound_ctrl:1
	v_pk_fma_f32 v[104:105], v[92:93], v[16:17], v[88:89] op_sel_hi:[1,0,1]
	v_pk_mul_f32 v[88:89], v[106:107], v[110:111] op_sel_hi:[1,0]
	v_add_f32_dpp v96, v96, v96 row_half_mirror row_mask:0xf bank_mask:0xf bound_ctrl:1
	v_pk_fma_f32 v[106:107], v[94:95], v[16:17], v[88:89] op_sel_hi:[1,0,1]
	s_waitcnt lgkmcnt(0)
; DI float row16_sum(float v) { v += dppf(v, 0); v += dppf(v, 1); v += dppf(v, 2); v += dppf(v, 3); return v; }
; DI void mamba_scan(CP p, const Ptrs& w, int l, int item, float* sm) {
;     ...
;     MStep cur = lds_step(bf, 0);
; #pragma unroll
;     for (int j = 0; j < 16; ++j) {
;       MStep nxt = cur;
;       if (j + 1 < 16) nxt = lds_step(bf, j + 1);
;       f2v ya = M0 * cur.C0.xy + M1 * cur.C0.zw, yb = M2 * cur.C1.xy + M3 * cur.C1.zw;
;       ya += yb;
;       float yp = row16_sum(ya.x + ya.y);
;       float y = cur.sc.x * yp + cur.xq * cur.sc.y + cur.ds;
;       const float dA = cur.sc.x, xq = cur.xq;
;       M0 = M0 * dA + xq * cur.B0.xy; M1 = M1 * dA + xq * cur.B0.zw;
;       M2 = M2 * dA + xq * cur.B1.xy; M3 = M3 * dA + xq * cur.B1.zw;
;       sy[(ng == 0 ? j * 16 : 0) + ysel] = y;
;       cur = nxt;
	v_pk_mul_f32 v[40:41], v[108:109], v[40:41]
	v_add_f32_dpp v96, v96, v96 row_mirror row_mask:0xf bank_mask:0xf bound_ctrl:1
	v_mul_f32_e32 v96, v110, v96
	v_pk_fma_f32 v[38:39], v[46:47], v[38:39], v[40:41]
	v_fmac_f32_e32 v96, v16, v111
	v_pk_fma_f32 v[38:39], v[106:107], v[44:45], v[38:39]
	v_add_f32_e32 v96, v114, v96
	v_pk_fma_f32 v[38:39], v[104:105], v[42:43], v[38:39]
	ds_write_b32 v67, v96 offset:37376
	v_add_f32_e32 v38, v38, v39
	ds_read_b128 v[88:91], v59 offset:3584
	ds_read_b128 v[92:95], v59 offset:3600
	v_add_f32_dpp v38, v38, v38 quad_perm:[1,0,3,2] row_mask:0xf bank_mask:0xf bound_ctrl:1
	ds_read_b128 v[96:99], v59 offset:11776
	ds_read_b128 v[100:103], v59 offset:11792
	v_add_f32_dpp v38, v38, v38 quad_perm:[2,3,0,1] row_mask:0xf bank_mask:0xf bound_ctrl:1
	ds_read_b32 v16, v60 offset:16832
	ds_read_b32 v114, v60 offset:17856
	v_add_f32_dpp v38, v38, v38 row_half_mirror row_mask:0xf bank_mask:0xf bound_ctrl:1
	ds_read_b64 v[110:111], v157 offset:18544
	s_nop 0
	v_add_f32_dpp v38, v38, v38 row_mirror row_mask:0xf bank_mask:0xf bound_ctrl:1
	v_mul_f32_e32 v38, v112, v38
	v_fmac_f32_e32 v38, v8, v113
	v_add_f32_e32 v40, v115, v38
	v_pk_mul_f32 v[38:39], v[46:47], v[112:113] op_sel_hi:[1,0]
	ds_write_b32 v68, v40 offset:37376
	v_pk_fma_f32 v[46:47], v[22:23], v[8:9], v[38:39] op_sel_hi:[1,0,1]
	v_pk_mul_f32 v[22:23], v[108:109], v[112:113] op_sel_hi:[1,0]
	v_pk_fma_f32 v[108:109], v[24:25], v[8:9], v[22:23] op_sel_hi:[1,0,1]
	v_pk_mul_f32 v[22:23], v[104:105], v[112:113] op_sel_hi:[1,0]
	v_pk_fma_f32 v[104:105], v[26:27], v[8:9], v[22:23] op_sel_hi:[1,0,1]
	v_pk_mul_f32 v[22:23], v[106:107], v[112:113] op_sel_hi:[1,0]
	v_pk_fma_f32 v[106:107], v[28:29], v[8:9], v[22:23] op_sel_hi:[1,0,1]
	ds_read_b128 v[22:25], v59 offset:4096
	ds_read_b128 v[26:29], v59 offset:4112
	ds_read_b128 v[38:41], v59 offset:12288
	ds_read_b128 v[42:45], v59 offset:12304
	ds_read_b32 v8, v60 offset:16896
	ds_read_b32 v115, v60 offset:17920
	s_waitcnt lgkmcnt(14)
	ds_read_b64 v[112:113], v157 offset:18560
	s_waitcnt lgkmcnt(7)
	v_pk_mul_f32 v[98:99], v[108:109], v[98:99]
	v_pk_fma_f32 v[96:97], v[46:47], v[96:97], v[98:99]
	v_pk_fma_f32 v[96:97], v[106:107], v[102:103], v[96:97]
	v_pk_fma_f32 v[96:97], v[104:105], v[100:101], v[96:97]
	v_pk_mul_f32 v[46:47], v[46:47], v[110:111] op_sel_hi:[1,0]
	v_add_f32_e32 v96, v96, v97
	v_pk_fma_f32 v[46:47], v[88:89], v[16:17], v[46:47] op_sel_hi:[1,0,1]
	v_pk_mul_f32 v[88:89], v[108:109], v[110:111] op_sel_hi:[1,0]
	v_add_f32_dpp v96, v96, v96 quad_perm:[1,0,3,2] row_mask:0xf bank_mask:0xf bound_ctrl:1
	v_pk_fma_f32 v[108:109], v[90:91], v[16:17], v[88:89] op_sel_hi:[1,0,1]
	v_pk_mul_f32 v[88:89], v[104:105], v[110:111] op_sel_hi:[1,0]
	v_add_f32_dpp v96, v96, v96 quad_perm:[2,3,0,1] row_mask:0xf bank_mask:0xf bound_ctrl:1
	v_pk_fma_f32 v[104:105], v[92:93], v[16:17], v[88:89] op_sel_hi:[1,0,1]
	v_pk_mul_f32 v[88:89], v[106:107], v[110:111] op_sel_hi:[1,0]
	v_add_f32_dpp v96, v96, v96 row_half_mirror row_mask:0xf bank_mask:0xf bound_ctrl:1
	v_pk_fma_f32 v[106:107], v[94:95], v[16:17], v[88:89] op_sel_hi:[1,0,1]
	s_waitcnt lgkmcnt(0)
	v_pk_mul_f32 v[40:41], v[108:109], v[40:41]
	v_add_f32_dpp v96, v96, v96 row_mirror row_mask:0xf bank_mask:0xf bound_ctrl:1
	v_mul_f32_e32 v96, v110, v96
	v_pk_fma_f32 v[38:39], v[46:47], v[38:39], v[40:41]
	v_fmac_f32_e32 v96, v16, v111
	v_pk_fma_f32 v[38:39], v[106:107], v[44:45], v[38:39]
	v_add_f32_e32 v96, v114, v96
	v_pk_fma_f32 v[38:39], v[104:105], v[42:43], v[38:39]
	ds_write_b32 v70, v96 offset:37376
	v_add_f32_e32 v38, v38, v39
	ds_read_b128 v[88:91], v59 offset:4608
	ds_read_b128 v[92:95], v59 offset:4624
	v_add_f32_dpp v38, v38, v38 quad_perm:[1,0,3,2] row_mask:0xf bank_mask:0xf bound_ctrl:1
	ds_read_b128 v[96:99], v59 offset:12800
	ds_read_b128 v[100:103], v59 offset:12816
	v_add_f32_dpp v38, v38, v38 quad_perm:[2,3,0,1] row_mask:0xf bank_mask:0xf bound_ctrl:1
	ds_read_b32 v16, v60 offset:16960
	ds_read_b32 v114, v60 offset:17984
	v_add_f32_dpp v38, v38, v38 row_half_mirror row_mask:0xf bank_mask:0xf bound_ctrl:1
	ds_read_b64 v[110:111], v157 offset:18576
	s_nop 0
	v_add_f32_dpp v38, v38, v38 row_mirror row_mask:0xf bank_mask:0xf bound_ctrl:1
	v_mul_f32_e32 v38, v112, v38
	v_fmac_f32_e32 v38, v8, v113
	v_add_f32_e32 v40, v115, v38
	v_pk_mul_f32 v[38:39], v[46:47], v[112:113] op_sel_hi:[1,0]
	ds_write_b32 v71, v40 offset:37376
	v_pk_fma_f32 v[46:47], v[22:23], v[8:9], v[38:39] op_sel_hi:[1,0,1]
	v_pk_mul_f32 v[22:23], v[108:109], v[112:113] op_sel_hi:[1,0]
	v_pk_fma_f32 v[108:109], v[24:25], v[8:9], v[22:23] op_sel_hi:[1,0,1]
	v_pk_mul_f32 v[22:23], v[104:105], v[112:113] op_sel_hi:[1,0]
	v_pk_fma_f32 v[104:105], v[26:27], v[8:9], v[22:23] op_sel_hi:[1,0,1]
	v_pk_mul_f32 v[22:23], v[106:107], v[112:113] op_sel_hi:[1,0]
	v_pk_fma_f32 v[106:107], v[28:29], v[8:9], v[22:23] op_sel_hi:[1,0,1]
	ds_read_b128 v[22:25], v59 offset:5120
	ds_read_b128 v[26:29], v59 offset:5136
	ds_read_b128 v[38:41], v59 offset:13312
	ds_read_b128 v[42:45], v59 offset:13328
	ds_read_b32 v8, v60 offset:17024
	ds_read_b32 v115, v60 offset:18048
	s_waitcnt lgkmcnt(14)
	ds_read_b64 v[112:113], v157 offset:18592
	s_waitcnt lgkmcnt(7)
; DI float row16_sum(float v) { v += dppf(v, 0); v += dppf(v, 1); v += dppf(v, 2); v += dppf(v, 3); return v; }
; DI void mamba_scan(CP p, const Ptrs& w, int l, int item, float* sm) {
;     ...
;     MStep cur = lds_step(bf, 0);
; #pragma unroll
;     for (int j = 0; j < 16; ++j) {
;       MStep nxt = cur;
;       if (j + 1 < 16) nxt = lds_step(bf, j + 1);
;       f2v ya = M0 * cur.C0.xy + M1 * cur.C0.zw, yb = M2 * cur.C1.xy + M3 * cur.C1.zw;
;       ya += yb;
;       float yp = row16_sum(ya.x + ya.y);
;       float y = cur.sc.x * yp + cur.xq * cur.sc.y + cur.ds;
;       const float dA = cur.sc.x, xq = cur.xq;
;       M0 = M0 * dA + xq * cur.B0.xy; M1 = M1 * dA + xq * cur.B0.zw;
;       M2 = M2 * dA + xq * cur.B1.xy; M3 = M3 * dA + xq * cur.B1.zw;
;       sy[(ng == 0 ? j * 16 : 0) + ysel] = y;
;       cur = nxt;
	v_pk_mul_f32 v[98:99], v[108:109], v[98:99]
	v_pk_fma_f32 v[96:97], v[46:47], v[96:97], v[98:99]
	v_pk_fma_f32 v[96:97], v[106:107], v[102:103], v[96:97]
	v_pk_fma_f32 v[96:97], v[104:105], v[100:101], v[96:97]
	v_add_f32_e32 v96, v96, v97
	v_pk_mul_f32 v[46:47], v[46:47], v[110:111] op_sel_hi:[1,0]
	v_pk_fma_f32 v[46:47], v[88:89], v[16:17], v[46:47] op_sel_hi:[1,0,1]
	v_add_f32_dpp v96, v96, v96 quad_perm:[1,0,3,2] row_mask:0xf bank_mask:0xf bound_ctrl:1
	v_pk_mul_f32 v[88:89], v[108:109], v[110:111] op_sel_hi:[1,0]
	v_pk_fma_f32 v[108:109], v[90:91], v[16:17], v[88:89] op_sel_hi:[1,0,1]
	v_add_f32_dpp v96, v96, v96 quad_perm:[2,3,0,1] row_mask:0xf bank_mask:0xf bound_ctrl:1
	v_pk_mul_f32 v[88:89], v[104:105], v[110:111] op_sel_hi:[1,0]
	v_pk_fma_f32 v[104:105], v[92:93], v[16:17], v[88:89] op_sel_hi:[1,0,1]
	v_add_f32_dpp v96, v96, v96 row_half_mirror row_mask:0xf bank_mask:0xf bound_ctrl:1
	v_pk_mul_f32 v[88:89], v[106:107], v[110:111] op_sel_hi:[1,0]
	v_pk_fma_f32 v[106:107], v[94:95], v[16:17], v[88:89] op_sel_hi:[1,0,1]
	v_add_f32_dpp v96, v96, v96 row_mirror row_mask:0xf bank_mask:0xf bound_ctrl:1
	v_mul_f32_e32 v96, v110, v96
	v_fmac_f32_e32 v96, v16, v111
	v_add_f32_e32 v96, v114, v96
	ds_write_b32 v73, v96 offset:37376
	ds_read_b128 v[88:91], v59 offset:5632
	s_waitcnt lgkmcnt(2)
	v_pk_mul_f32 v[40:41], v[108:109], v[40:41]
	ds_read_b128 v[92:95], v59 offset:5648
	v_pk_fma_f32 v[38:39], v[46:47], v[38:39], v[40:41]
	ds_read_b128 v[96:99], v59 offset:13824
	v_pk_fma_f32 v[38:39], v[106:107], v[44:45], v[38:39]
	ds_read_b128 v[100:103], v59 offset:13840
	v_pk_fma_f32 v[38:39], v[104:105], v[42:43], v[38:39]
	ds_read_b32 v16, v60 offset:17088
	v_add_f32_e32 v38, v38, v39
	ds_read_b32 v114, v60 offset:18112
	ds_read_b64 v[110:111], v157 offset:18608
	v_add_f32_dpp v38, v38, v38 quad_perm:[1,0,3,2] row_mask:0xf bank_mask:0xf bound_ctrl:1
	s_nop 1
	v_add_f32_dpp v38, v38, v38 quad_perm:[2,3,0,1] row_mask:0xf bank_mask:0xf bound_ctrl:1
	s_nop 1
	v_add_f32_dpp v38, v38, v38 row_half_mirror row_mask:0xf bank_mask:0xf bound_ctrl:1
	s_nop 1
	v_add_f32_dpp v38, v38, v38 row_mirror row_mask:0xf bank_mask:0xf bound_ctrl:1
	v_mul_f32_e32 v38, v112, v38
	v_fmac_f32_e32 v38, v8, v113
	v_add_f32_e32 v40, v115, v38
	v_pk_mul_f32 v[38:39], v[46:47], v[112:113] op_sel_hi:[1,0]
	ds_write_b32 v74, v40 offset:37376
	v_pk_fma_f32 v[46:47], v[22:23], v[8:9], v[38:39] op_sel_hi:[1,0,1]
	v_pk_mul_f32 v[22:23], v[108:109], v[112:113] op_sel_hi:[1,0]
	v_pk_fma_f32 v[108:109], v[24:25], v[8:9], v[22:23] op_sel_hi:[1,0,1]
	v_pk_mul_f32 v[22:23], v[104:105], v[112:113] op_sel_hi:[1,0]
	v_pk_fma_f32 v[104:105], v[26:27], v[8:9], v[22:23] op_sel_hi:[1,0,1]
	v_pk_mul_f32 v[22:23], v[106:107], v[112:113] op_sel_hi:[1,0]
	v_pk_fma_f32 v[106:107], v[28:29], v[8:9], v[22:23] op_sel_hi:[1,0,1]
	ds_read_b128 v[22:25], v59 offset:6144
	ds_read_b128 v[26:29], v59 offset:6160
	ds_read_b128 v[38:41], v59 offset:14336
	ds_read_b128 v[42:45], v59 offset:14352
	ds_read_b32 v8, v60 offset:17152
	ds_read_b32 v115, v60 offset:18176
	s_waitcnt lgkmcnt(14)
	ds_read_b64 v[112:113], v157 offset:18624
	s_waitcnt lgkmcnt(7)
	v_pk_mul_f32 v[98:99], v[108:109], v[98:99]
	v_pk_fma_f32 v[96:97], v[46:47], v[96:97], v[98:99]
	v_pk_fma_f32 v[96:97], v[106:107], v[102:103], v[96:97]
	v_pk_fma_f32 v[96:97], v[104:105], v[100:101], v[96:97]
	v_add_f32_e32 v96, v96, v97
	v_pk_mul_f32 v[46:47], v[46:47], v[110:111] op_sel_hi:[1,0]
	v_pk_fma_f32 v[46:47], v[88:89], v[16:17], v[46:47] op_sel_hi:[1,0,1]
	v_add_f32_dpp v96, v96, v96 quad_perm:[1,0,3,2] row_mask:0xf bank_mask:0xf bound_ctrl:1
	v_pk_mul_f32 v[88:89], v[108:109], v[110:111] op_sel_hi:[1,0]
	v_pk_fma_f32 v[108:109], v[90:91], v[16:17], v[88:89] op_sel_hi:[1,0,1]
	v_add_f32_dpp v96, v96, v96 quad_perm:[2,3,0,1] row_mask:0xf bank_mask:0xf bound_ctrl:1
	v_pk_mul_f32 v[88:89], v[104:105], v[110:111] op_sel_hi:[1,0]
	v_pk_fma_f32 v[104:105], v[92:93], v[16:17], v[88:89] op_sel_hi:[1,0,1]
	v_add_f32_dpp v96, v96, v96 row_half_mirror row_mask:0xf bank_mask:0xf bound_ctrl:1
	v_pk_mul_f32 v[88:89], v[106:107], v[110:111] op_sel_hi:[1,0]
	v_pk_fma_f32 v[106:107], v[94:95], v[16:17], v[88:89] op_sel_hi:[1,0,1]
	v_add_f32_dpp v96, v96, v96 row_mirror row_mask:0xf bank_mask:0xf bound_ctrl:1
	v_mul_f32_e32 v96, v110, v96
	v_fmac_f32_e32 v96, v16, v111
	v_add_f32_e32 v96, v114, v96
	ds_write_b32 v75, v96 offset:37376
	ds_read_b128 v[88:91], v59 offset:6656
	ds_read_b128 v[92:95], v59 offset:6672
	ds_read_b128 v[96:99], v59 offset:14848
	ds_read_b128 v[100:103], v59 offset:14864
	ds_read_b32 v16, v60 offset:17216
	s_waitcnt lgkmcnt(6)
	v_pk_mul_f32 v[40:41], v[108:109], v[40:41]
	ds_read_b32 v118, v60 offset:18240
	v_pk_fma_f32 v[38:39], v[46:47], v[38:39], v[40:41]
	ds_read_b64 v[116:117], v157 offset:18640
	v_pk_fma_f32 v[38:39], v[106:107], v[44:45], v[38:39]
	v_pk_fma_f32 v[38:39], v[104:105], v[42:43], v[38:39]
	v_add_f32_e32 v38, v38, v39
	s_nop 1
	v_add_f32_dpp v38, v38, v38 quad_perm:[1,0,3,2] row_mask:0xf bank_mask:0xf bound_ctrl:1
	s_nop 1
	v_add_f32_dpp v38, v38, v38 quad_perm:[2,3,0,1] row_mask:0xf bank_mask:0xf bound_ctrl:1
	s_nop 1
	v_add_f32_dpp v38, v38, v38 row_half_mirror row_mask:0xf bank_mask:0xf bound_ctrl:1
	s_nop 1
	v_add_f32_dpp v38, v38, v38 row_mirror row_mask:0xf bank_mask:0xf bound_ctrl:1
	v_mul_f32_e32 v38, v112, v38
	v_fmac_f32_e32 v38, v8, v113
	v_add_f32_e32 v40, v115, v38
	v_pk_mul_f32 v[38:39], v[46:47], v[112:113] op_sel_hi:[1,0]
	ds_write_b32 v76, v40 offset:37376
	v_pk_fma_f32 v[22:23], v[22:23], v[8:9], v[38:39] op_sel_hi:[1,0,1]
	v_pk_mul_f32 v[38:39], v[108:109], v[112:113] op_sel_hi:[1,0]
	ds_read_b128 v[42:45], v59 offset:7168
	v_pk_fma_f32 v[24:25], v[24:25], v[8:9], v[38:39] op_sel_hi:[1,0,1]
	v_pk_mul_f32 v[38:39], v[104:105], v[112:113] op_sel_hi:[1,0]
	v_pk_fma_f32 v[26:27], v[26:27], v[8:9], v[38:39] op_sel_hi:[1,0,1]
	v_pk_mul_f32 v[38:39], v[106:107], v[112:113] op_sel_hi:[1,0]
	ds_read_b128 v[104:107], v59 offset:7184
	v_pk_fma_f32 v[28:29], v[28:29], v[8:9], v[38:39] op_sel_hi:[1,0,1]
	ds_read_b128 v[108:111], v59 offset:15360
	ds_read_b128 v[112:115], v59 offset:15376
	ds_read_b32 v8, v60 offset:17280
	ds_read_b32 v119, v60 offset:18304
	s_waitcnt lgkmcnt(14)
; DI float bf2f(bf16_t h) { return __uint_as_float(((unsigned)h) << 16); }
; DI float siluf(float x) { return x * sigmf(x); }
; DI float row16_sum(float v) { v += dppf(v, 0); v += dppf(v, 1); v += dppf(v, 2); v += dppf(v, 3); return v; }
; DI void mamba_scan(CP p, const Ptrs& w, int l, int item, float* sm) {
;     ...
;   auto stage = [&](const MPre& P, float* bufp) {
; #pragma unroll
;     for (int i = 0; i < 2; ++i) {
;       int idx = tid + 256 * i, j = idx >> 5, q = idx & 31;
;       float f[8];
;       unpack8(P.pbq[i], f);
;       float* d = bufp + (q < 16 ? 0 : 2048) + j * 128 + (q & 15) * 8;
;       *(float4*)d = make_float4(f[0], f[1], f[2], f[3]);
;       *(float4*)(d + 4) = make_float4(f[4], f[5], f[6], f[7]);
;     }
;     {
;       float xs = siluf(wX0 * P.pxm[0] * bf2f(P.px[0]) + wX1 * bf2f(P.px[1]) + wX2 * P.pxm[1] * bf2f(P.px[2]) + bX);
;       bufp[4096 + xj * 16 + xp] = xs * P.pdt[0];
;       bufp[4096 + 256 + xj * 16 + xp] = Dsk * xs;
;       if (xp == 0) *(float4*)(bufp + 4096 + 512 + xj * 4) = make_float4(P.pdt[1], P.pdt[2], 0.f, 0.f);
;     }
;     ...
;       f2v ya = M0 * cur.C0.xy + M1 * cur.C0.zw, yb = M2 * cur.C1.xy + M3 * cur.C1.zw;
;       ya += yb;
;       float yp = row16_sum(ya.x + ya.y);
;       float y = cur.sc.x * yp + cur.xq * cur.sc.y + cur.ds;
;       const float dA = cur.sc.x, xq = cur.xq;
;       M0 = M0 * dA + xq * cur.B0.xy; M1 = M1 * dA + xq * cur.B0.zw;
;       M2 = M2 * dA + xq * cur.B1.xy; M3 = M3 * dA + xq * cur.B1.zw;
;       sy[(ng == 0 ? j * 16 : 0) + ysel] = y;
;       cur = nxt;
	ds_read_b64 v[46:47], v157 offset:18656
	s_waitcnt lgkmcnt(6)
	v_pk_mul_f32 v[38:39], v[24:25], v[98:99]
	v_pk_mul_f32 v[40:41], v[28:29], v[102:103]
	v_pk_fma_f32 v[38:39], v[22:23], v[96:97], v[38:39]
	v_pk_fma_f32 v[40:41], v[26:27], v[100:101], v[40:41]
	v_pk_add_f32 v[38:39], v[38:39], v[40:41]
	v_add_f32_e32 v38, v38, v39
	v_pk_mul_f32 v[22:23], v[22:23], v[116:117] op_sel_hi:[1,0]
	v_pk_fma_f32 v[40:41], v[88:89], v[16:17], v[22:23] op_sel_hi:[1,0,1]
	v_add_f32_dpp v38, v38, v38 quad_perm:[1,0,3,2] row_mask:0xf bank_mask:0xf bound_ctrl:1
	v_pk_mul_f32 v[22:23], v[24:25], v[116:117] op_sel_hi:[1,0]
	v_pk_fma_f32 v[96:97], v[90:91], v[16:17], v[22:23] op_sel_hi:[1,0,1]
	v_add_f32_dpp v38, v38, v38 quad_perm:[2,3,0,1] row_mask:0xf bank_mask:0xf bound_ctrl:1
	v_pk_mul_f32 v[22:23], v[26:27], v[116:117] op_sel_hi:[1,0]
	v_pk_fma_f32 v[98:99], v[92:93], v[16:17], v[22:23] op_sel_hi:[1,0,1]
	v_add_f32_dpp v38, v38, v38 row_half_mirror row_mask:0xf bank_mask:0xf bound_ctrl:1
	v_pk_mul_f32 v[22:23], v[28:29], v[116:117] op_sel_hi:[1,0]
	v_pk_fma_f32 v[100:101], v[94:95], v[16:17], v[22:23] op_sel_hi:[1,0,1]
	v_add_f32_dpp v38, v38, v38 row_mirror row_mask:0xf bank_mask:0xf bound_ctrl:1
	v_mul_f32_e32 v38, v116, v38
	v_fmac_f32_e32 v38, v16, v117
	v_add_f32_e32 v38, v118, v38
	ds_write_b32 v77, v38 offset:37376
	ds_read_b128 v[26:29], v59 offset:7680
	ds_read_b128 v[22:25], v59 offset:7696
	ds_read_b128 v[88:91], v59 offset:15872
	ds_read_b128 v[92:95], v59 offset:15888
	ds_read_b32 v16, v60 offset:17344
	ds_read_b32 v116, v60 offset:18368
	ds_read_b64 v[38:39], v157 offset:18672
	s_waitcnt lgkmcnt(8)
	v_pk_mul_f32 v[102:103], v[96:97], v[110:111]
	v_pk_fma_f32 v[102:103], v[40:41], v[108:109], v[102:103]
	v_pk_fma_f32 v[102:103], v[100:101], v[114:115], v[102:103]
	v_pk_fma_f32 v[102:103], v[98:99], v[112:113], v[102:103]
	v_pk_mul_f32 v[40:41], v[40:41], v[46:47] op_sel_hi:[1,0]
	v_add_f32_e32 v102, v102, v103
	v_pk_fma_f32 v[42:43], v[42:43], v[8:9], v[40:41] op_sel_hi:[1,0,1]
	v_pk_mul_f32 v[40:41], v[96:97], v[46:47] op_sel_hi:[1,0]
	v_add_f32_dpp v102, v102, v102 quad_perm:[1,0,3,2] row_mask:0xf bank_mask:0xf bound_ctrl:1
	v_pk_fma_f32 v[44:45], v[44:45], v[8:9], v[40:41] op_sel_hi:[1,0,1]
	v_pk_mul_f32 v[40:41], v[98:99], v[46:47] op_sel_hi:[1,0]
	v_add_f32_dpp v102, v102, v102 quad_perm:[2,3,0,1] row_mask:0xf bank_mask:0xf bound_ctrl:1
	v_pk_fma_f32 v[40:41], v[104:105], v[8:9], v[40:41] op_sel_hi:[1,0,1]
	s_waitcnt lgkmcnt(0)
	v_pk_mul_f32 v[90:91], v[44:45], v[90:91]
	v_add_f32_dpp v102, v102, v102 row_half_mirror row_mask:0xf bank_mask:0xf bound_ctrl:1
	v_pk_fma_f32 v[88:89], v[42:43], v[88:89], v[90:91]
	s_nop 0
	v_add_f32_dpp v102, v102, v102 row_mirror row_mask:0xf bank_mask:0xf bound_ctrl:1
	v_mul_f32_e32 v102, v46, v102
	v_fmac_f32_e32 v102, v8, v47
	v_pk_mul_f32 v[46:47], v[100:101], v[46:47] op_sel_hi:[1,0]
	v_add_f32_e32 v102, v119, v102
	v_pk_fma_f32 v[46:47], v[106:107], v[8:9], v[46:47] op_sel_hi:[1,0,1]
	ds_write_b32 v78, v102 offset:37376
	v_pk_fma_f32 v[88:89], v[46:47], v[94:95], v[88:89]
	v_pk_fma_f32 v[88:89], v[40:41], v[92:93], v[88:89]
	s_waitcnt vmcnt(8)
	v_lshlrev_b32_e32 v90, 16, v5
	v_add_f32_e32 v8, v88, v89
	v_lshlrev_b32_e32 v88, 16, v4
	v_and_b32_e32 v89, 0xffff0000, v4
	v_add_f32_dpp v8, v8, v8 quad_perm:[1,0,3,2] row_mask:0xf bank_mask:0xf bound_ctrl:1
	v_and_b32_e32 v91, 0xffff0000, v5
	v_lshlrev_b32_e32 v4, 16, v6
	v_add_f32_dpp v8, v8, v8 quad_perm:[2,3,0,1] row_mask:0xf bank_mask:0xf bound_ctrl:1
	v_and_b32_e32 v5, 0xffff0000, v6
	v_lshlrev_b32_e32 v6, 16, v7
	v_add_f32_dpp v8, v8, v8 row_half_mirror row_mask:0xf bank_mask:0xf bound_ctrl:1
	v_and_b32_e32 v7, 0xffff0000, v7
	s_nop 0
	v_add_f32_dpp v8, v8, v8 row_mirror row_mask:0xf bank_mask:0xf bound_ctrl:1
	s_waitcnt lgkmcnt(1)
	v_mul_f32_e32 v8, v38, v8
	v_fmac_f32_e32 v8, v16, v39
	v_add_f32_e32 v8, v116, v8
	ds_write_b32 v80, v8 offset:37376
	ds_write_b128 v58, v[88:91] offset:18688
	ds_write_b128 v58, v[4:7] offset:18704
	v_lshlrev_b32_e32 v4, 16, v0
	v_and_b32_e32 v5, 0xffff0000, v0
	v_lshlrev_b32_e32 v6, 16, v1
	v_and_b32_e32 v7, 0xffff0000, v1
	v_mul_f32_e32 v0, v49, v87
	v_lshlrev_b32_e32 v1, 16, v64
	v_mul_f32_e32 v0, v0, v1
	v_lshlrev_b32_e32 v1, 16, v69
	v_fmac_f32_e32 v0, v50, v1
	v_mul_f32_e32 v1, v51, v86
	v_lshlrev_b32_e32 v8, 16, v79
	v_fmac_f32_e32 v0, v1, v8
	v_add_f32_e32 v8, v52, v0
	v_mul_f32_e32 v0, 0xbfb8aa3b, v8
	v_exp_f32_e32 v39, v0
	v_lshlrev_b32_e32 v0, 16, v2
	v_and_b32_e32 v1, 0xffff0000, v2
	v_lshlrev_b32_e32 v2, 16, v3
	v_add_f32_e32 v39, 1.0, v39
	v_rcp_f32_e32 v39, v39
	v_and_b32_e32 v3, 0xffff0000, v3
	ds_write_b128 v58, v[4:7] offset:22784
	ds_write_b128 v58, v[0:3] offset:22800
	v_mul_f32_e32 v0, v8, v39
	v_mul_f32_e32 v1, v10, v0
	v_mul_f32_e32 v0, v53, v0
	ds_write2st64_b32 v57, v1, v0 offset0:137 offset1:141
	s_and_saveexec_b64 s[4:5], vcc
	v_mov_b32_e32 v8, v11
	v_mov_b32_e32 v10, v157
	v_mov_b32_e32 v11, v157
	ds_write_b128 v72, v[8:11] offset:37120
	s_or_b64 exec, exec, s[4:5]
	s_add_i32 s7, s7, 2
	v_pk_mul_f32 v[0:1], v[42:43], v[38:39] op_sel_hi:[1,0]
	s_min_u32 s4, s7, 0x20c
	v_pk_fma_f32 v[108:109], v[26:27], v[16:17], v[0:1] op_sel_hi:[1,0,1]
	v_pk_mul_f32 v[0:1], v[44:45], v[38:39] op_sel_hi:[1,0]
	s_lshl_b32 s4, s4, 4
	v_pk_fma_f32 v[110:111], v[28:29], v[16:17], v[0:1] op_sel_hi:[1,0,1]
	v_pk_mul_f32 v[0:1], v[40:41], v[38:39] op_sel_hi:[1,0]
	v_cndmask_b32_e64 v87, 1.0, 0, s[42:43]
	v_pk_fma_f32 v[112:113], v[22:23], v[16:17], v[0:1] op_sel_hi:[1,0,1]
	v_pk_mul_f32 v[0:1], v[46:47], v[38:39] op_sel_hi:[1,0]
	s_add_i32 s42, s4, 48
	v_pk_fma_f32 v[46:47], v[24:25], v[16:17], v[0:1] op_sel_hi:[1,0,1]
; DI void mamba_scan(CP p, const Ptrs& w, int l, int item, float* sm) {
;     ...
;   auto load = [&](int c, MPre& P) {
; #pragma unroll
;     for (int i = 0; i < 2; ++i) {
;       int idx = tid + 256 * i, j = idx >> 5, q = idx & 31;
;       int ii = pos2i(c * 16 + j, dir);
;       P.pbq[i] = *(const uint4*)(mbc + ((size_t)b * TPB + ii) * 512 + (q < 16 ? 0 : 256) + gp * 128 + (q & 15) * 8);
;     }
;     {
;       int pos = c * 16 + xj, ii = pos2i(pos, dir);
;       size_t tok = (size_t)b * TPB + ii;
;       const bf16_t* prw = w.pC + tok * SPC;
;       bool hp = (ii != 0) && (ii != CTXL), hn = (ii != CTXL - 1) && (ii != TPB - 1);
;       P.px[0] = prw[chX + (hp ? -SPC : 0)]; P.px[1] = prw[chX]; P.px[2] = prw[chX + (hn ? SPC : 0)];
;       P.pxm[0] = hp ? 1.f : 0.f; P.pxm[1] = hn ? 1.f : 0.f;
;       float2 dd = *(const float2*)(w.mdt + (tok * 16 + dir * 8 + hd) * 2);
;       P.pdt[0] = dd.x; P.pdt[1] = dd.y; P.pdt[2] = w.mcb[tok * 2 + gp];
;     }
;     ...
;   auto flush = [&](int c) {
;     {
;       int j = tid >> 4, rr = tid & 15;
;       int ii = pos2i(c * 16 + j, dir);
;       yout[((size_t)b * TPB + ii) * 512 + hd * 64 + pq * 16 + rr] = f2bf(sY[(c & 1) * 256 + j * 16 + rr]);
;     }
;   };
;   __syncthreads();
;   load(0, PA);
;   stage(PA, sm);
;   load(1, PB);
;   __syncthreads();
;   const int NCH = TPB / 16;
;   auto run_chunk = [&](int c, const float* bf, float* sy) {
;     flush(max(c - 1, 0));
;     MStep cur = lds_step(bf, 0);
; #pragma unroll
;     for (int j = 0; j < 16; ++j) {
;       MStep nxt = cur;
;       if (j + 1 < 16) nxt = lds_step(bf, j + 1);
;       f2v ya = M0 * cur.C0.xy + M1 * cur.C0.zw, yb = M2 * cur.C1.xy + M3 * cur.C1.zw;
;       ya += yb;
;       float yp = row16_sum(ya.x + ya.y);
;       float y = cur.sc.x * yp + cur.xq * cur.sc.y + cur.ds;
;       const float dA = cur.sc.x, xq = cur.xq;
;       M0 = M0 * dA + xq * cur.B0.xy; M1 = M1 * dA + xq * cur.B0.zw;
;       M2 = M2 * dA + xq * cur.B1.xy; M3 = M3 * dA + xq * cur.B1.zw;
;       sy[(ng == 0 ? j * 16 : 0) + ysel] = y;
;       cur = nxt;
;     }
;   };
;   for (int c = 0; c < NCH; c += 2) {
;     load(min(c + 2, NCH - 1), PA);
;     run_chunk(c, sm, sY);
;     stage(PB, sm + BUF);
;     __syncthreads();
;     load(min(c + 3, NCH - 1), PB);
;     run_chunk(c + 1, sm + BUF, sY + 256);
	v_add_u32_e32 v0, s42, v55
	v_cmp_lt_i32_e64 s[4:5], s37, v0
	v_add_u32_e32 v2, s42, v56
	v_add_u32_e32 v8, s42, v54
	v_cndmask_b32_e64 v1, v231, v232, s[4:5]
	v_cmp_lt_i32_e64 s[4:5], s37, v2
	v_sub_u32_e32 v1, v1, v0
	v_cndmask_b32_e64 v0, v1, v0, s[40:41]
	v_cndmask_b32_e64 v3, v231, v232, s[4:5]
	v_cmp_lt_i32_e64 s[4:5], s37, v8
	v_sub_u32_e32 v3, v3, v2
	v_cndmask_b32_e64 v2, v3, v2, s[40:41]
	v_cndmask_b32_e64 v9, v231, v232, s[4:5]
	v_sub_u32_e32 v9, v9, v8
	v_cndmask_b32_e64 v8, v9, v8, s[40:41]
	v_ashrrev_i32_e32 v9, 31, v8
	v_lshl_add_u64 v[10:11], v[8:9], 0, s[90:91]
	v_and_b32_e32 v9, 0xfffffeff, v8
	v_cmp_eq_u32_e64 s[42:43], 0, v9
	v_ashrrev_i32_e32 v1, 31, v0
	v_ashrrev_i32_e32 v3, 31, v2
	v_mov_b64_e32 v[22:23], s[48:49]
	v_and_b32_e32 v16, 0xffffdfff, v8
	v_cndmask_b32_e64 v8, v233, 0, s[42:43]
	v_lshl_add_u64 v[0:1], v[0:1], 0, s[90:91]
	v_lshl_add_u64 v[2:3], v[2:3], 0, s[90:91]
	v_mad_u64_u32 v[22:23], s[4:5], v10, s92, v[22:23]
	v_add_u32_e32 v8, v8, v48
	v_cndmask_b32_e64 v86, 1.0, 0, s[44:45]
	v_lshlrev_b64 v[0:1], 10, v[0:1]
	v_lshlrev_b64 v[2:3], 10, v[2:3]
	v_mad_i32_i24 v23, v11, s92, v23
	v_ashrrev_i32_e32 v9, 31, v8
	v_cmp_eq_u32_e64 s[44:45], s37, v16
	v_lshlrev_b64 v[26:27], 7, v[10:11]
	v_lshl_add_u64 v[0:1], v[30:31], 0, v[0:1]
	v_lshl_add_u64 v[2:3], v[30:31], 0, v[2:3]
	v_lshl_add_u64 v[8:9], v[8:9], 1, v[22:23]
	v_lshl_add_u64 v[22:23], v[22:23], 0, v[156:157]
	v_cndmask_b32_e64 v24, v234, 0, s[44:45]
	v_mov_b32_e32 v25, v157
	v_lshl_or_b32 v26, s6, 3, v26
	s_waitcnt lgkmcnt(0)
	s_barrier
	global_load_dwordx4 v[4:7], v[0:1], off
	s_nop 0
	global_load_dwordx4 v[0:3], v[2:3], off
	v_lshl_add_u64 v[24:25], v[22:23], 0, v[24:25]
	v_lshl_add_u64 v[26:27], s[46:47], 0, v[26:27]
	v_lshl_add_u64 v[28:29], v[10:11], 3, s[50:51]
	global_load_ushort v64, v[8:9], off
	global_load_ushort v69, v[22:23], off
	global_load_ushort v79, v[24:25], off
	global_load_dwordx2 v[10:11], v[26:27], off
	s_nop 0
	global_load_dword v9, v[28:29], off
	v_cmp_lt_i32_e64 s[4:5], s37, v82
	ds_read_b32 v8, v57 offset:37376
	ds_read_b128 v[22:25], v59 offset:18688
	v_cndmask_b32_e64 v16, v231, v232, s[4:5]
	v_add_u32_e32 v16, v16, v81
	v_cndmask_b32_e64 v26, v16, v82, s[40:41]
	v_ashrrev_i32_e32 v27, 31, v26
	v_lshl_add_u64 v[26:27], v[26:27], 0, s[90:91]
	v_lshlrev_b64 v[26:27], 10, v[26:27]
	s_waitcnt lgkmcnt(1)
	v_cvt_pk_bf16_f32 v8, v8, s0
	v_lshl_add_u64 v[26:27], v[34:35], 0, v[26:27]
	global_store_short v[26:27], v8, off
	s_waitcnt lgkmcnt(0)
	v_add_u32_e32 v8, 0x8800, v60
	s_mov_b32 s4, 0x9000
	ds_read2_b32 v[114:115], v8 offset0:64 offset1:80
	v_add_u32_e32 v8, 0x8c00, v60
	ds_read2_b32 v[116:117], v8 offset0:64 offset1:80
	v_add_u32_e64 v8, s4, 0
	ds_read2_b64 v[26:29], v8 offset0:32 offset1:34
	ds_read_b128 v[38:41], v59 offset:18704
	ds_read_b128 v[42:45], v59 offset:19200
	ds_read_b128 v[88:91], v59 offset:26880
	ds_read_b128 v[92:95], v59 offset:19216
	ds_read_b128 v[96:99], v59 offset:26896
	ds_read_b128 v[100:103], v59 offset:27392
	ds_read_b128 v[104:107], v59 offset:27408
	s_waitcnt lgkmcnt(4)
	v_pk_mul_f32 v[90:91], v[110:111], v[90:91]
	v_pk_fma_f32 v[88:89], v[108:109], v[88:89], v[90:91]
	s_waitcnt lgkmcnt(2)
	v_pk_fma_f32 v[88:89], v[46:47], v[98:99], v[88:89]
	v_pk_fma_f32 v[88:89], v[112:113], v[96:97], v[88:89]
	v_add_f32_e32 v8, v88, v89
	v_pk_mul_f32 v[88:89], v[108:109], v[26:27] op_sel_hi:[1,0]
	v_pk_fma_f32 v[108:109], v[22:23], v[114:115], v[88:89] op_sel_hi:[1,0,1]
	v_add_f32_dpp v8, v8, v8 quad_perm:[1,0,3,2] row_mask:0xf bank_mask:0xf bound_ctrl:1
	v_pk_mul_f32 v[22:23], v[110:111], v[26:27] op_sel_hi:[1,0]
	v_pk_fma_f32 v[110:111], v[24:25], v[114:115], v[22:23] op_sel_hi:[1,0,1]
	v_add_f32_dpp v8, v8, v8 quad_perm:[2,3,0,1] row_mask:0xf bank_mask:0xf bound_ctrl:1
	v_pk_mul_f32 v[22:23], v[112:113], v[26:27] op_sel_hi:[1,0]
	s_waitcnt lgkmcnt(0)
	v_pk_mul_f32 v[102:103], v[110:111], v[102:103]
	v_add_f32_dpp v8, v8, v8 row_half_mirror row_mask:0xf bank_mask:0xf bound_ctrl:1
	v_pk_fma_f32 v[112:113], v[38:39], v[114:115], v[22:23] op_sel_hi:[1,0,1]
	v_pk_mul_f32 v[22:23], v[46:47], v[26:27] op_sel_hi:[1,0]
	v_add_f32_dpp v8, v8, v8 row_mirror row_mask:0xf bank_mask:0xf bound_ctrl:1
	v_mul_f32_e32 v8, v26, v8
	v_fmac_f32_e32 v8, v114, v27
	v_pk_fma_f32 v[26:27], v[40:41], v[114:115], v[22:23] op_sel_hi:[1,0,1]
	v_add_f32_e32 v8, v116, v8
	ds_write_b32 v61, v8 offset:38400
	ds_read_b128 v[22:25], v59 offset:19712
	ds_read_b128 v[38:41], v59 offset:19728
	ds_read_b128 v[88:91], v59 offset:27904
	v_pk_fma_f32 v[100:101], v[108:109], v[100:101], v[102:103]
	ds_read_b128 v[96:99], v59 offset:27920
	v_pk_fma_f32 v[100:101], v[26:27], v[106:107], v[100:101]
	ds_read_b32 v8, v60 offset:35200
	v_pk_fma_f32 v[100:101], v[112:113], v[104:105], v[100:101]
	ds_read_b32 v114, v60 offset:36224
	v_add_f32_e32 v16, v100, v101
	ds_read_b64 v[46:47], v157 offset:37152
	v_pk_mul_f32 v[100:101], v[108:109], v[28:29] op_sel_hi:[1,0]
	v_add_f32_dpp v16, v16, v16 quad_perm:[1,0,3,2] row_mask:0xf bank_mask:0xf bound_ctrl:1
	v_pk_mul_f32 v[26:27], v[26:27], v[28:29] op_sel_hi:[1,0]
	s_nop 0
	v_add_f32_dpp v16, v16, v16 quad_perm:[2,3,0,1] row_mask:0xf bank_mask:0xf bound_ctrl:1
	s_nop 1
	v_add_f32_dpp v16, v16, v16 row_half_mirror row_mask:0xf bank_mask:0xf bound_ctrl:1
	s_nop 1
	v_add_f32_dpp v16, v16, v16 row_mirror row_mask:0xf bank_mask:0xf bound_ctrl:1
	v_mul_f32_e32 v16, v28, v16
	v_fmac_f32_e32 v16, v115, v29
	v_add_f32_e32 v102, v117, v16
	v_mov_b32_e32 v16, v115
	ds_write_b32 v62, v102 offset:38400
	v_pk_fma_f32 v[104:105], v[42:43], v[16:17], v[100:101] op_sel_hi:[1,0,1]
	v_pk_mul_f32 v[42:43], v[110:111], v[28:29] op_sel_hi:[1,0]
	v_pk_fma_f32 v[110:111], v[94:95], v[16:17], v[26:27] op_sel_hi:[1,0,1]
	v_pk_fma_f32 v[106:107], v[44:45], v[16:17], v[42:43] op_sel_hi:[1,0,1]
	v_pk_mul_f32 v[42:43], v[112:113], v[28:29] op_sel_hi:[1,0]
	ds_read_b128 v[26:29], v59 offset:20224
	v_pk_fma_f32 v[108:109], v[92:93], v[16:17], v[42:43] op_sel_hi:[1,0,1]
	ds_read_b128 v[42:45], v59 offset:20240
	ds_read_b128 v[92:95], v59 offset:28416
	ds_read_b128 v[100:103], v59 offset:28432
	ds_read_b32 v16, v60 offset:35264
	ds_read_b32 v115, v60 offset:36288
	s_waitcnt lgkmcnt(14)
; DI float row16_sum(float v) { v += dppf(v, 0); v += dppf(v, 1); v += dppf(v, 2); v += dppf(v, 3); return v; }
; DI void mamba_scan(CP p, const Ptrs& w, int l, int item, float* sm) {
;     ...
;   auto run_chunk = [&](int c, const float* bf, float* sy) {
;     flush(max(c - 1, 0));
;     MStep cur = lds_step(bf, 0);
; #pragma unroll
;     for (int j = 0; j < 16; ++j) {
;       MStep nxt = cur;
;       if (j + 1 < 16) nxt = lds_step(bf, j + 1);
;       f2v ya = M0 * cur.C0.xy + M1 * cur.C0.zw, yb = M2 * cur.C1.xy + M3 * cur.C1.zw;
;       ya += yb;
;       float yp = row16_sum(ya.x + ya.y);
;       float y = cur.sc.x * yp + cur.xq * cur.sc.y + cur.ds;
;       const float dA = cur.sc.x, xq = cur.xq;
;       M0 = M0 * dA + xq * cur.B0.xy; M1 = M1 * dA + xq * cur.B0.zw;
;       M2 = M2 * dA + xq * cur.B1.xy; M3 = M3 * dA + xq * cur.B1.zw;
;       sy[(ng == 0 ? j * 16 : 0) + ysel] = y;
;       cur = nxt;
;     }
	ds_read_b64 v[112:113], v157 offset:37168
	s_waitcnt lgkmcnt(7)
	v_pk_mul_f32 v[90:91], v[106:107], v[90:91]
	v_pk_fma_f32 v[88:89], v[104:105], v[88:89], v[90:91]
	v_pk_fma_f32 v[88:89], v[110:111], v[98:99], v[88:89]
	v_pk_fma_f32 v[88:89], v[108:109], v[96:97], v[88:89]
	v_add_f32_e32 v88, v88, v89
	s_nop 1
	v_add_f32_dpp v88, v88, v88 quad_perm:[1,0,3,2] row_mask:0xf bank_mask:0xf bound_ctrl:1
	s_nop 1
	v_add_f32_dpp v88, v88, v88 quad_perm:[2,3,0,1] row_mask:0xf bank_mask:0xf bound_ctrl:1
	s_nop 1
	v_add_f32_dpp v88, v88, v88 row_half_mirror row_mask:0xf bank_mask:0xf bound_ctrl:1
	s_nop 1
	v_add_f32_dpp v88, v88, v88 row_mirror row_mask:0xf bank_mask:0xf bound_ctrl:1
	v_mul_f32_e32 v88, v46, v88
	v_fmac_f32_e32 v88, v8, v47
	v_add_f32_e32 v90, v114, v88
	v_pk_mul_f32 v[88:89], v[104:105], v[46:47] op_sel_hi:[1,0]
	ds_write_b32 v63, v90 offset:38400
	v_pk_fma_f32 v[104:105], v[22:23], v[8:9], v[88:89] op_sel_hi:[1,0,1]
	v_pk_mul_f32 v[22:23], v[106:107], v[46:47] op_sel_hi:[1,0]
	v_pk_fma_f32 v[106:107], v[24:25], v[8:9], v[22:23] op_sel_hi:[1,0,1]
	v_pk_mul_f32 v[22:23], v[108:109], v[46:47] op_sel_hi:[1,0]
	v_pk_fma_f32 v[108:109], v[38:39], v[8:9], v[22:23] op_sel_hi:[1,0,1]
	v_pk_mul_f32 v[22:23], v[110:111], v[46:47] op_sel_hi:[1,0]
	v_pk_fma_f32 v[46:47], v[40:41], v[8:9], v[22:23] op_sel_hi:[1,0,1]
	ds_read_b128 v[22:25], v59 offset:20736
	s_waitcnt lgkmcnt(2)
	v_pk_mul_f32 v[94:95], v[106:107], v[94:95]
	ds_read_b128 v[38:41], v59 offset:20752
	v_pk_fma_f32 v[92:93], v[104:105], v[92:93], v[94:95]
	ds_read_b128 v[88:91], v59 offset:28928
	v_pk_fma_f32 v[92:93], v[46:47], v[102:103], v[92:93]
	ds_read_b128 v[96:99], v59 offset:28944
	v_pk_fma_f32 v[92:93], v[108:109], v[100:101], v[92:93]
	ds_read_b32 v8, v60 offset:35328
	v_add_f32_e32 v92, v92, v93
	ds_read_b32 v114, v60 offset:36352
	ds_read_b64 v[110:111], v157 offset:37184
	v_add_f32_dpp v92, v92, v92 quad_perm:[1,0,3,2] row_mask:0xf bank_mask:0xf bound_ctrl:1
	s_nop 1
	v_add_f32_dpp v92, v92, v92 quad_perm:[2,3,0,1] row_mask:0xf bank_mask:0xf bound_ctrl:1
	s_nop 1
	v_add_f32_dpp v92, v92, v92 row_half_mirror row_mask:0xf bank_mask:0xf bound_ctrl:1
	s_nop 1
	v_add_f32_dpp v92, v92, v92 row_mirror row_mask:0xf bank_mask:0xf bound_ctrl:1
	v_mul_f32_e32 v92, v112, v92
	v_fmac_f32_e32 v92, v16, v113
	v_add_f32_e32 v94, v115, v92
	v_pk_mul_f32 v[92:93], v[104:105], v[112:113] op_sel_hi:[1,0]
	ds_write_b32 v65, v94 offset:38400
	v_pk_fma_f32 v[104:105], v[26:27], v[16:17], v[92:93] op_sel_hi:[1,0,1]
	v_pk_mul_f32 v[26:27], v[106:107], v[112:113] op_sel_hi:[1,0]
	v_pk_fma_f32 v[106:107], v[28:29], v[16:17], v[26:27] op_sel_hi:[1,0,1]
	v_pk_mul_f32 v[26:27], v[108:109], v[112:113] op_sel_hi:[1,0]
	v_pk_fma_f32 v[108:109], v[42:43], v[16:17], v[26:27] op_sel_hi:[1,0,1]
	v_pk_mul_f32 v[26:27], v[46:47], v[112:113] op_sel_hi:[1,0]
	v_pk_fma_f32 v[46:47], v[44:45], v[16:17], v[26:27] op_sel_hi:[1,0,1]
	ds_read_b128 v[26:29], v59 offset:21248
	ds_read_b128 v[42:45], v59 offset:21264
	ds_read_b128 v[92:95], v59 offset:29440
	ds_read_b128 v[100:103], v59 offset:29456
	ds_read_b32 v16, v60 offset:35392
	ds_read_b32 v115, v60 offset:36416
	s_waitcnt lgkmcnt(14)
	ds_read_b64 v[112:113], v157 offset:37200
	s_waitcnt lgkmcnt(7)
	v_pk_mul_f32 v[90:91], v[106:107], v[90:91]
	v_pk_fma_f32 v[88:89], v[104:105], v[88:89], v[90:91]
	v_pk_fma_f32 v[88:89], v[46:47], v[98:99], v[88:89]
	v_pk_fma_f32 v[88:89], v[108:109], v[96:97], v[88:89]
	v_add_f32_e32 v88, v88, v89
	s_nop 1
	v_add_f32_dpp v88, v88, v88 quad_perm:[1,0,3,2] row_mask:0xf bank_mask:0xf bound_ctrl:1
	s_nop 1
	v_add_f32_dpp v88, v88, v88 quad_perm:[2,3,0,1] row_mask:0xf bank_mask:0xf bound_ctrl:1
	s_nop 1
	v_add_f32_dpp v88, v88, v88 row_half_mirror row_mask:0xf bank_mask:0xf bound_ctrl:1
	s_nop 1
	v_add_f32_dpp v88, v88, v88 row_mirror row_mask:0xf bank_mask:0xf bound_ctrl:1
	v_mul_f32_e32 v88, v110, v88
	v_fmac_f32_e32 v88, v8, v111
	v_add_f32_e32 v90, v114, v88
	v_pk_mul_f32 v[88:89], v[104:105], v[110:111] op_sel_hi:[1,0]
	ds_write_b32 v66, v90 offset:38400
	v_pk_fma_f32 v[104:105], v[22:23], v[8:9], v[88:89] op_sel_hi:[1,0,1]
	v_pk_mul_f32 v[22:23], v[106:107], v[110:111] op_sel_hi:[1,0]
	v_pk_fma_f32 v[106:107], v[24:25], v[8:9], v[22:23] op_sel_hi:[1,0,1]
	v_pk_mul_f32 v[22:23], v[108:109], v[110:111] op_sel_hi:[1,0]
	v_pk_fma_f32 v[108:109], v[38:39], v[8:9], v[22:23] op_sel_hi:[1,0,1]
	v_pk_mul_f32 v[22:23], v[46:47], v[110:111] op_sel_hi:[1,0]
	v_pk_fma_f32 v[46:47], v[40:41], v[8:9], v[22:23] op_sel_hi:[1,0,1]
	ds_read_b128 v[22:25], v59 offset:21760
	ds_read_b128 v[38:41], v59 offset:21776
	s_waitcnt lgkmcnt(3)
	v_pk_mul_f32 v[94:95], v[106:107], v[94:95]
	ds_read_b128 v[88:91], v59 offset:29952
	v_pk_fma_f32 v[92:93], v[104:105], v[92:93], v[94:95]
	ds_read_b128 v[96:99], v59 offset:29968
	v_pk_fma_f32 v[92:93], v[46:47], v[102:103], v[92:93]
	ds_read_b32 v8, v60 offset:35456
	v_pk_fma_f32 v[92:93], v[108:109], v[100:101], v[92:93]
	ds_read_b32 v114, v60 offset:36480
	v_add_f32_e32 v92, v92, v93
	ds_read_b64 v[110:111], v157 offset:37216
	s_nop 0
	v_add_f32_dpp v92, v92, v92 quad_perm:[1,0,3,2] row_mask:0xf bank_mask:0xf bound_ctrl:1
	s_nop 1
	v_add_f32_dpp v92, v92, v92 quad_perm:[2,3,0,1] row_mask:0xf bank_mask:0xf bound_ctrl:1
	s_nop 1
	v_add_f32_dpp v92, v92, v92 row_half_mirror row_mask:0xf bank_mask:0xf bound_ctrl:1
	s_nop 1
	v_add_f32_dpp v92, v92, v92 row_mirror row_mask:0xf bank_mask:0xf bound_ctrl:1
	v_mul_f32_e32 v92, v112, v92
	v_fmac_f32_e32 v92, v16, v113
	v_add_f32_e32 v94, v115, v92
	v_pk_mul_f32 v[92:93], v[104:105], v[112:113] op_sel_hi:[1,0]
	ds_write_b32 v67, v94 offset:38400
	v_pk_fma_f32 v[104:105], v[26:27], v[16:17], v[92:93] op_sel_hi:[1,0,1]
	v_pk_mul_f32 v[26:27], v[106:107], v[112:113] op_sel_hi:[1,0]
	v_pk_fma_f32 v[106:107], v[28:29], v[16:17], v[26:27] op_sel_hi:[1,0,1]
	v_pk_mul_f32 v[26:27], v[108:109], v[112:113] op_sel_hi:[1,0]
	v_pk_fma_f32 v[108:109], v[42:43], v[16:17], v[26:27] op_sel_hi:[1,0,1]
	v_pk_mul_f32 v[26:27], v[46:47], v[112:113] op_sel_hi:[1,0]
	v_pk_fma_f32 v[46:47], v[44:45], v[16:17], v[26:27] op_sel_hi:[1,0,1]
	ds_read_b128 v[26:29], v59 offset:22272
	ds_read_b128 v[42:45], v59 offset:22288
	ds_read_b128 v[92:95], v59 offset:30464
	ds_read_b128 v[100:103], v59 offset:30480
	ds_read_b32 v16, v60 offset:35520
	ds_read_b32 v115, v60 offset:36544
	s_waitcnt lgkmcnt(14)
; DI float row16_sum(float v) { v += dppf(v, 0); v += dppf(v, 1); v += dppf(v, 2); v += dppf(v, 3); return v; }
; DI void mamba_scan(CP p, const Ptrs& w, int l, int item, float* sm) {
;     ...
;   auto run_chunk = [&](int c, const float* bf, float* sy) {
;     flush(max(c - 1, 0));
;     MStep cur = lds_step(bf, 0);
; #pragma unroll
;     for (int j = 0; j < 16; ++j) {
;       MStep nxt = cur;
;       if (j + 1 < 16) nxt = lds_step(bf, j + 1);
;       f2v ya = M0 * cur.C0.xy + M1 * cur.C0.zw, yb = M2 * cur.C1.xy + M3 * cur.C1.zw;
;       ya += yb;
;       float yp = row16_sum(ya.x + ya.y);
;       float y = cur.sc.x * yp + cur.xq * cur.sc.y + cur.ds;
;       const float dA = cur.sc.x, xq = cur.xq;
;       M0 = M0 * dA + xq * cur.B0.xy; M1 = M1 * dA + xq * cur.B0.zw;
;       M2 = M2 * dA + xq * cur.B1.xy; M3 = M3 * dA + xq * cur.B1.zw;
;       sy[(ng == 0 ? j * 16 : 0) + ysel] = y;
;       cur = nxt;
;     }
	ds_read_b64 v[112:113], v157 offset:37232
	s_waitcnt lgkmcnt(7)
	v_pk_mul_f32 v[90:91], v[106:107], v[90:91]
	v_pk_fma_f32 v[88:89], v[104:105], v[88:89], v[90:91]
	v_pk_fma_f32 v[88:89], v[46:47], v[98:99], v[88:89]
	v_pk_fma_f32 v[88:89], v[108:109], v[96:97], v[88:89]
	v_add_f32_e32 v88, v88, v89
	s_nop 1
	v_add_f32_dpp v88, v88, v88 quad_perm:[1,0,3,2] row_mask:0xf bank_mask:0xf bound_ctrl:1
	s_nop 1
	v_add_f32_dpp v88, v88, v88 quad_perm:[2,3,0,1] row_mask:0xf bank_mask:0xf bound_ctrl:1
	s_nop 1
	v_add_f32_dpp v88, v88, v88 row_half_mirror row_mask:0xf bank_mask:0xf bound_ctrl:1
	s_nop 1
	v_add_f32_dpp v88, v88, v88 row_mirror row_mask:0xf bank_mask:0xf bound_ctrl:1
	v_mul_f32_e32 v88, v110, v88
	v_fmac_f32_e32 v88, v8, v111
	v_add_f32_e32 v90, v114, v88
	v_pk_mul_f32 v[88:89], v[104:105], v[110:111] op_sel_hi:[1,0]
	ds_write_b32 v68, v90 offset:38400
	v_pk_fma_f32 v[104:105], v[22:23], v[8:9], v[88:89] op_sel_hi:[1,0,1]
	v_pk_mul_f32 v[22:23], v[106:107], v[110:111] op_sel_hi:[1,0]
	v_pk_fma_f32 v[106:107], v[24:25], v[8:9], v[22:23] op_sel_hi:[1,0,1]
	v_pk_mul_f32 v[22:23], v[108:109], v[110:111] op_sel_hi:[1,0]
	v_pk_fma_f32 v[108:109], v[38:39], v[8:9], v[22:23] op_sel_hi:[1,0,1]
	v_pk_mul_f32 v[22:23], v[46:47], v[110:111] op_sel_hi:[1,0]
	v_pk_fma_f32 v[46:47], v[40:41], v[8:9], v[22:23] op_sel_hi:[1,0,1]
	ds_read_b128 v[22:25], v59 offset:22784
	ds_read_b128 v[38:41], v59 offset:22800
	ds_read_b128 v[88:91], v59 offset:30976
	s_waitcnt lgkmcnt(4)
	v_pk_mul_f32 v[94:95], v[106:107], v[94:95]
	ds_read_b128 v[96:99], v59 offset:30992
	v_pk_fma_f32 v[92:93], v[104:105], v[92:93], v[94:95]
	ds_read_b32 v8, v60 offset:35584
	v_pk_fma_f32 v[92:93], v[46:47], v[102:103], v[92:93]
	ds_read_b32 v114, v60 offset:36608
	v_pk_fma_f32 v[92:93], v[108:109], v[100:101], v[92:93]
	ds_read_b64 v[110:111], v157 offset:37248
	v_add_f32_e32 v92, v92, v93
	s_nop 1
	v_add_f32_dpp v92, v92, v92 quad_perm:[1,0,3,2] row_mask:0xf bank_mask:0xf bound_ctrl:1
	s_nop 1
	v_add_f32_dpp v92, v92, v92 quad_perm:[2,3,0,1] row_mask:0xf bank_mask:0xf bound_ctrl:1
	s_nop 1
	v_add_f32_dpp v92, v92, v92 row_half_mirror row_mask:0xf bank_mask:0xf bound_ctrl:1
	s_nop 1
	v_add_f32_dpp v92, v92, v92 row_mirror row_mask:0xf bank_mask:0xf bound_ctrl:1
	v_mul_f32_e32 v92, v112, v92
	v_fmac_f32_e32 v92, v16, v113
	v_add_f32_e32 v94, v115, v92
	v_pk_mul_f32 v[92:93], v[104:105], v[112:113] op_sel_hi:[1,0]
	ds_write_b32 v70, v94 offset:38400
	v_pk_fma_f32 v[104:105], v[26:27], v[16:17], v[92:93] op_sel_hi:[1,0,1]
	v_pk_mul_f32 v[26:27], v[106:107], v[112:113] op_sel_hi:[1,0]
	v_pk_fma_f32 v[106:107], v[28:29], v[16:17], v[26:27] op_sel_hi:[1,0,1]
	v_pk_mul_f32 v[26:27], v[108:109], v[112:113] op_sel_hi:[1,0]
	v_pk_fma_f32 v[108:109], v[42:43], v[16:17], v[26:27] op_sel_hi:[1,0,1]
	v_pk_mul_f32 v[26:27], v[46:47], v[112:113] op_sel_hi:[1,0]
	v_pk_fma_f32 v[46:47], v[44:45], v[16:17], v[26:27] op_sel_hi:[1,0,1]
	ds_read_b128 v[26:29], v59 offset:23296
	ds_read_b128 v[42:45], v59 offset:23312
	ds_read_b128 v[92:95], v59 offset:31488
	ds_read_b128 v[100:103], v59 offset:31504
	ds_read_b32 v16, v60 offset:35648
	ds_read_b32 v115, v60 offset:36672
	s_waitcnt lgkmcnt(14)
	ds_read_b64 v[112:113], v157 offset:37264
	s_waitcnt lgkmcnt(7)
	v_pk_mul_f32 v[90:91], v[106:107], v[90:91]
	v_pk_fma_f32 v[88:89], v[104:105], v[88:89], v[90:91]
	v_pk_fma_f32 v[88:89], v[46:47], v[98:99], v[88:89]
	v_pk_fma_f32 v[88:89], v[108:109], v[96:97], v[88:89]
	v_add_f32_e32 v88, v88, v89
	s_nop 1
	v_add_f32_dpp v88, v88, v88 quad_perm:[1,0,3,2] row_mask:0xf bank_mask:0xf bound_ctrl:1
	s_nop 1
	v_add_f32_dpp v88, v88, v88 quad_perm:[2,3,0,1] row_mask:0xf bank_mask:0xf bound_ctrl:1
	s_nop 1
	v_add_f32_dpp v88, v88, v88 row_half_mirror row_mask:0xf bank_mask:0xf bound_ctrl:1
	s_nop 1
	v_add_f32_dpp v88, v88, v88 row_mirror row_mask:0xf bank_mask:0xf bound_ctrl:1
	v_mul_f32_e32 v88, v110, v88
	v_fmac_f32_e32 v88, v8, v111
	v_add_f32_e32 v90, v114, v88
	v_pk_mul_f32 v[88:89], v[104:105], v[110:111] op_sel_hi:[1,0]
	ds_write_b32 v71, v90 offset:38400
	v_pk_fma_f32 v[104:105], v[22:23], v[8:9], v[88:89] op_sel_hi:[1,0,1]
	v_pk_mul_f32 v[22:23], v[106:107], v[110:111] op_sel_hi:[1,0]
	v_pk_fma_f32 v[106:107], v[24:25], v[8:9], v[22:23] op_sel_hi:[1,0,1]
	v_pk_mul_f32 v[22:23], v[108:109], v[110:111] op_sel_hi:[1,0]
	v_pk_fma_f32 v[108:109], v[38:39], v[8:9], v[22:23] op_sel_hi:[1,0,1]
	v_pk_mul_f32 v[22:23], v[46:47], v[110:111] op_sel_hi:[1,0]
	v_pk_fma_f32 v[46:47], v[40:41], v[8:9], v[22:23] op_sel_hi:[1,0,1]
	ds_read_b128 v[22:25], v59 offset:23808
	ds_read_b128 v[38:41], v59 offset:23824
	ds_read_b128 v[88:91], v59 offset:32000
	ds_read_b128 v[96:99], v59 offset:32016
	s_waitcnt lgkmcnt(4)
	v_pk_mul_f32 v[94:95], v[106:107], v[94:95]
	ds_read_b32 v8, v60 offset:35712
	v_pk_fma_f32 v[92:93], v[104:105], v[92:93], v[94:95]
	ds_read_b32 v114, v60 offset:36736
	v_pk_fma_f32 v[92:93], v[46:47], v[102:103], v[92:93]
	ds_read_b64 v[110:111], v157 offset:37280
	v_pk_fma_f32 v[92:93], v[108:109], v[100:101], v[92:93]
	v_add_f32_e32 v92, v92, v93
	s_nop 1
	v_add_f32_dpp v92, v92, v92 quad_perm:[1,0,3,2] row_mask:0xf bank_mask:0xf bound_ctrl:1
	s_nop 1
	v_add_f32_dpp v92, v92, v92 quad_perm:[2,3,0,1] row_mask:0xf bank_mask:0xf bound_ctrl:1
	s_nop 1
	v_add_f32_dpp v92, v92, v92 row_half_mirror row_mask:0xf bank_mask:0xf bound_ctrl:1
	s_nop 1
	v_add_f32_dpp v92, v92, v92 row_mirror row_mask:0xf bank_mask:0xf bound_ctrl:1
	v_mul_f32_e32 v92, v112, v92
	v_fmac_f32_e32 v92, v16, v113
	v_add_f32_e32 v94, v115, v92
	v_pk_mul_f32 v[92:93], v[104:105], v[112:113] op_sel_hi:[1,0]
	ds_write_b32 v73, v94 offset:38400
	v_pk_fma_f32 v[104:105], v[26:27], v[16:17], v[92:93] op_sel_hi:[1,0,1]
	v_pk_mul_f32 v[26:27], v[106:107], v[112:113] op_sel_hi:[1,0]
	v_pk_fma_f32 v[106:107], v[28:29], v[16:17], v[26:27] op_sel_hi:[1,0,1]
	v_pk_mul_f32 v[26:27], v[108:109], v[112:113] op_sel_hi:[1,0]
	v_pk_fma_f32 v[108:109], v[42:43], v[16:17], v[26:27] op_sel_hi:[1,0,1]
	v_pk_mul_f32 v[26:27], v[46:47], v[112:113] op_sel_hi:[1,0]
	v_pk_fma_f32 v[46:47], v[44:45], v[16:17], v[26:27] op_sel_hi:[1,0,1]
	ds_read_b128 v[26:29], v59 offset:24320
	ds_read_b128 v[42:45], v59 offset:24336
	ds_read_b128 v[92:95], v59 offset:32512
	ds_read_b128 v[100:103], v59 offset:32528
	ds_read_b32 v16, v60 offset:35776
	ds_read_b32 v115, v60 offset:36800
	s_waitcnt lgkmcnt(6)
; DI float row16_sum(float v) { v += dppf(v, 0); v += dppf(v, 1); v += dppf(v, 2); v += dppf(v, 3); return v; }
; DI void mamba_scan(CP p, const Ptrs& w, int l, int item, float* sm) {
;     ...
;   auto run_chunk = [&](int c, const float* bf, float* sy) {
;     flush(max(c - 1, 0));
;     MStep cur = lds_step(bf, 0);
; #pragma unroll
;     for (int j = 0; j < 16; ++j) {
;       MStep nxt = cur;
;       if (j + 1 < 16) nxt = lds_step(bf, j + 1);
;       f2v ya = M0 * cur.C0.xy + M1 * cur.C0.zw, yb = M2 * cur.C1.xy + M3 * cur.C1.zw;
;       ya += yb;
;       float yp = row16_sum(ya.x + ya.y);
;       float y = cur.sc.x * yp + cur.xq * cur.sc.y + cur.ds;
;       const float dA = cur.sc.x, xq = cur.xq;
;       M0 = M0 * dA + xq * cur.B0.xy; M1 = M1 * dA + xq * cur.B0.zw;
;       M2 = M2 * dA + xq * cur.B1.xy; M3 = M3 * dA + xq * cur.B1.zw;
;       sy[(ng == 0 ? j * 16 : 0) + ysel] = y;
;       cur = nxt;
;     }
	v_pk_mul_f32 v[90:91], v[106:107], v[90:91]
	ds_read_b64 v[112:113], v157 offset:37296
	v_pk_fma_f32 v[88:89], v[104:105], v[88:89], v[90:91]
	v_pk_fma_f32 v[88:89], v[46:47], v[98:99], v[88:89]
	v_pk_fma_f32 v[88:89], v[108:109], v[96:97], v[88:89]
	v_add_f32_e32 v88, v88, v89
	s_nop 1
	v_add_f32_dpp v88, v88, v88 quad_perm:[1,0,3,2] row_mask:0xf bank_mask:0xf bound_ctrl:1
	s_nop 1
	v_add_f32_dpp v88, v88, v88 quad_perm:[2,3,0,1] row_mask:0xf bank_mask:0xf bound_ctrl:1
	s_nop 1
	v_add_f32_dpp v88, v88, v88 row_half_mirror row_mask:0xf bank_mask:0xf bound_ctrl:1
	s_nop 1
	v_add_f32_dpp v88, v88, v88 row_mirror row_mask:0xf bank_mask:0xf bound_ctrl:1
	v_mul_f32_e32 v88, v110, v88
	v_fmac_f32_e32 v88, v8, v111
	v_add_f32_e32 v90, v114, v88
	v_pk_mul_f32 v[88:89], v[104:105], v[110:111] op_sel_hi:[1,0]
	ds_write_b32 v74, v90 offset:38400
	v_pk_fma_f32 v[104:105], v[22:23], v[8:9], v[88:89] op_sel_hi:[1,0,1]
	v_pk_mul_f32 v[22:23], v[106:107], v[110:111] op_sel_hi:[1,0]
	v_pk_fma_f32 v[106:107], v[24:25], v[8:9], v[22:23] op_sel_hi:[1,0,1]
	v_pk_mul_f32 v[22:23], v[108:109], v[110:111] op_sel_hi:[1,0]
	v_pk_fma_f32 v[108:109], v[38:39], v[8:9], v[22:23] op_sel_hi:[1,0,1]
	v_pk_mul_f32 v[22:23], v[46:47], v[110:111] op_sel_hi:[1,0]
	v_pk_fma_f32 v[46:47], v[40:41], v[8:9], v[22:23] op_sel_hi:[1,0,1]
	ds_read_b128 v[22:25], v59 offset:24832
	ds_read_b128 v[38:41], v59 offset:24848
	ds_read_b128 v[88:91], v59 offset:33024
	ds_read_b128 v[96:99], v59 offset:33040
	ds_read_b32 v8, v60 offset:35840
	s_waitcnt lgkmcnt(5)
	v_pk_mul_f32 v[94:95], v[106:107], v[94:95]
	ds_read_b32 v114, v60 offset:36864
	v_pk_fma_f32 v[92:93], v[104:105], v[92:93], v[94:95]
	ds_read_b64 v[110:111], v157 offset:37312
	v_pk_fma_f32 v[92:93], v[46:47], v[102:103], v[92:93]
	v_pk_fma_f32 v[92:93], v[108:109], v[100:101], v[92:93]
	v_add_f32_e32 v92, v92, v93
	s_nop 1
	v_add_f32_dpp v92, v92, v92 quad_perm:[1,0,3,2] row_mask:0xf bank_mask:0xf bound_ctrl:1
	s_nop 1
	v_add_f32_dpp v92, v92, v92 quad_perm:[2,3,0,1] row_mask:0xf bank_mask:0xf bound_ctrl:1
	s_nop 1
	v_add_f32_dpp v92, v92, v92 row_half_mirror row_mask:0xf bank_mask:0xf bound_ctrl:1
	s_nop 1
	v_add_f32_dpp v92, v92, v92 row_mirror row_mask:0xf bank_mask:0xf bound_ctrl:1
	v_mul_f32_e32 v92, v112, v92
	v_fmac_f32_e32 v92, v16, v113
	v_add_f32_e32 v94, v115, v92
	v_pk_mul_f32 v[92:93], v[104:105], v[112:113] op_sel_hi:[1,0]
	ds_write_b32 v75, v94 offset:38400
	v_pk_fma_f32 v[104:105], v[26:27], v[16:17], v[92:93] op_sel_hi:[1,0,1]
	v_pk_mul_f32 v[26:27], v[106:107], v[112:113] op_sel_hi:[1,0]
	v_pk_fma_f32 v[106:107], v[28:29], v[16:17], v[26:27] op_sel_hi:[1,0,1]
	v_pk_mul_f32 v[26:27], v[108:109], v[112:113] op_sel_hi:[1,0]
	v_pk_fma_f32 v[108:109], v[42:43], v[16:17], v[26:27] op_sel_hi:[1,0,1]
	v_pk_mul_f32 v[26:27], v[46:47], v[112:113] op_sel_hi:[1,0]
	v_pk_fma_f32 v[46:47], v[44:45], v[16:17], v[26:27] op_sel_hi:[1,0,1]
	ds_read_b128 v[26:29], v59 offset:25344
	ds_read_b128 v[42:45], v59 offset:25360
	ds_read_b128 v[92:95], v59 offset:33536
	ds_read_b128 v[100:103], v59 offset:33552
	ds_read_b32 v16, v60 offset:35904
	s_waitcnt lgkmcnt(5)
	v_pk_mul_f32 v[90:91], v[106:107], v[90:91]
	ds_read_b32 v116, v60 offset:36928
	v_pk_fma_f32 v[88:89], v[104:105], v[88:89], v[90:91]
	ds_read_b64 v[112:113], v157 offset:37328
	v_pk_fma_f32 v[88:89], v[46:47], v[98:99], v[88:89]
	v_pk_fma_f32 v[88:89], v[108:109], v[96:97], v[88:89]
	v_pk_mul_f32 v[46:47], v[46:47], v[110:111] op_sel_hi:[1,0]
	v_add_f32_e32 v88, v88, v89
	v_pk_fma_f32 v[40:41], v[40:41], v[8:9], v[46:47] op_sel_hi:[1,0,1]
	s_nop 0
	v_add_f32_dpp v88, v88, v88 quad_perm:[1,0,3,2] row_mask:0xf bank_mask:0xf bound_ctrl:1
	s_nop 1
	v_add_f32_dpp v88, v88, v88 quad_perm:[2,3,0,1] row_mask:0xf bank_mask:0xf bound_ctrl:1
	s_nop 1
	v_add_f32_dpp v88, v88, v88 row_half_mirror row_mask:0xf bank_mask:0xf bound_ctrl:1
	s_nop 1
	v_add_f32_dpp v88, v88, v88 row_mirror row_mask:0xf bank_mask:0xf bound_ctrl:1
	v_mul_f32_e32 v88, v110, v88
	v_fmac_f32_e32 v88, v8, v111
	v_add_f32_e32 v90, v114, v88
	v_pk_mul_f32 v[88:89], v[104:105], v[110:111] op_sel_hi:[1,0]
	ds_write_b32 v76, v90 offset:38400
	v_pk_fma_f32 v[22:23], v[22:23], v[8:9], v[88:89] op_sel_hi:[1,0,1]
	v_pk_mul_f32 v[88:89], v[106:107], v[110:111] op_sel_hi:[1,0]
	v_pk_fma_f32 v[24:25], v[24:25], v[8:9], v[88:89] op_sel_hi:[1,0,1]
	v_pk_mul_f32 v[88:89], v[108:109], v[110:111] op_sel_hi:[1,0]
	v_pk_fma_f32 v[38:39], v[38:39], v[8:9], v[88:89] op_sel_hi:[1,0,1]
	ds_read_b128 v[88:91], v59 offset:25856
	ds_read_b128 v[96:99], v59 offset:25872
	ds_read_b128 v[104:107], v59 offset:34048
	ds_read_b128 v[108:111], v59 offset:34064
	ds_read_b32 v46, v60 offset:35968
	ds_read_b32 v47, v60 offset:36992
	ds_read_b64 v[114:115], v157 offset:37344
	s_waitcnt lgkmcnt(7)
; DI float bf2f(bf16_t h) { return __uint_as_float(((unsigned)h) << 16); }
; DI float siluf(float x) { return x * sigmf(x); }
; DI float row16_sum(float v) { v += dppf(v, 0); v += dppf(v, 1); v += dppf(v, 2); v += dppf(v, 3); return v; }
; DI void mamba_scan(CP p, const Ptrs& w, int l, int item, float* sm) {
;     ...
;   auto stage = [&](const MPre& P, float* bufp) {
; #pragma unroll
;     for (int i = 0; i < 2; ++i) {
;       int idx = tid + 256 * i, j = idx >> 5, q = idx & 31;
;       float f[8];
;       unpack8(P.pbq[i], f);
;       float* d = bufp + (q < 16 ? 0 : 2048) + j * 128 + (q & 15) * 8;
;       *(float4*)d = make_float4(f[0], f[1], f[2], f[3]);
;       *(float4*)(d + 4) = make_float4(f[4], f[5], f[6], f[7]);
;     }
;     {
;       float xs = siluf(wX0 * P.pxm[0] * bf2f(P.px[0]) + wX1 * bf2f(P.px[1]) + wX2 * P.pxm[1] * bf2f(P.px[2]) + bX);
;       bufp[4096 + xj * 16 + xp] = xs * P.pdt[0];
;       bufp[4096 + 256 + xj * 16 + xp] = Dsk * xs;
;       if (xp == 0) *(float4*)(bufp + 4096 + 512 + xj * 4) = make_float4(P.pdt[1], P.pdt[2], 0.f, 0.f);
;     }
;   };
;     ...
;   auto run_chunk = [&](int c, const float* bf, float* sy) {
;     flush(max(c - 1, 0));
;     MStep cur = lds_step(bf, 0);
; #pragma unroll
;     for (int j = 0; j < 16; ++j) {
;       MStep nxt = cur;
;       if (j + 1 < 16) nxt = lds_step(bf, j + 1);
;       f2v ya = M0 * cur.C0.xy + M1 * cur.C0.zw, yb = M2 * cur.C1.xy + M3 * cur.C1.zw;
;       ya += yb;
;       float yp = row16_sum(ya.x + ya.y);
;       float y = cur.sc.x * yp + cur.xq * cur.sc.y + cur.ds;
;       const float dA = cur.sc.x, xq = cur.xq;
;       M0 = M0 * dA + xq * cur.B0.xy; M1 = M1 * dA + xq * cur.B0.zw;
;       M2 = M2 * dA + xq * cur.B1.xy; M3 = M3 * dA + xq * cur.B1.zw;
;       sy[(ng == 0 ? j * 16 : 0) + ysel] = y;
;       cur = nxt;
;     }
	v_pk_mul_f32 v[94:95], v[24:25], v[94:95]
	v_pk_fma_f32 v[92:93], v[22:23], v[92:93], v[94:95]
	v_pk_fma_f32 v[92:93], v[40:41], v[102:103], v[92:93]
	v_pk_fma_f32 v[92:93], v[38:39], v[100:101], v[92:93]
	v_pk_mul_f32 v[22:23], v[22:23], v[112:113] op_sel_hi:[1,0]
	v_add_f32_e32 v8, v92, v93
	s_nop 1
	v_add_f32_dpp v8, v8, v8 quad_perm:[1,0,3,2] row_mask:0xf bank_mask:0xf bound_ctrl:1
	s_nop 1
	v_add_f32_dpp v8, v8, v8 quad_perm:[2,3,0,1] row_mask:0xf bank_mask:0xf bound_ctrl:1
	s_nop 1
	v_add_f32_dpp v8, v8, v8 row_half_mirror row_mask:0xf bank_mask:0xf bound_ctrl:1
	s_nop 1
	v_add_f32_dpp v8, v8, v8 row_mirror row_mask:0xf bank_mask:0xf bound_ctrl:1
	v_mul_f32_e32 v8, v112, v8
	v_fmac_f32_e32 v8, v16, v113
	v_add_f32_e32 v8, v116, v8
	v_pk_fma_f32 v[116:117], v[26:27], v[16:17], v[22:23] op_sel_hi:[1,0,1]
	v_pk_mul_f32 v[22:23], v[24:25], v[112:113] op_sel_hi:[1,0]
	ds_write_b32 v77, v8 offset:38400
	v_pk_fma_f32 v[118:119], v[28:29], v[16:17], v[22:23] op_sel_hi:[1,0,1]
	v_pk_mul_f32 v[22:23], v[38:39], v[112:113] op_sel_hi:[1,0]
	ds_read_b128 v[26:29], v59 offset:26368
	v_pk_fma_f32 v[120:121], v[42:43], v[16:17], v[22:23] op_sel_hi:[1,0,1]
	v_pk_mul_f32 v[22:23], v[40:41], v[112:113] op_sel_hi:[1,0]
	v_pk_fma_f32 v[112:113], v[44:45], v[16:17], v[22:23] op_sel_hi:[1,0,1]
	ds_read_b128 v[22:25], v59 offset:26384
	ds_read_b128 v[92:95], v59 offset:34560
	ds_read_b128 v[100:103], v59 offset:34576
	ds_read_b32 v8, v60 offset:36032
	ds_read_b32 v16, v60 offset:37056
	s_waitcnt lgkmcnt(6)
	v_pk_mul_f32 v[40:41], v[118:119], v[106:107]
	ds_read_b64 v[38:39], v157 offset:37360
	v_pk_fma_f32 v[40:41], v[116:117], v[104:105], v[40:41]
	v_pk_fma_f32 v[40:41], v[112:113], v[110:111], v[40:41]
	v_pk_fma_f32 v[40:41], v[120:121], v[108:109], v[40:41]
	v_add_f32_e32 v40, v40, v41
	s_nop 1
	v_add_f32_dpp v40, v40, v40 quad_perm:[1,0,3,2] row_mask:0xf bank_mask:0xf bound_ctrl:1
	s_nop 1
	v_add_f32_dpp v40, v40, v40 quad_perm:[2,3,0,1] row_mask:0xf bank_mask:0xf bound_ctrl:1
	s_nop 1
	v_add_f32_dpp v40, v40, v40 row_half_mirror row_mask:0xf bank_mask:0xf bound_ctrl:1
	s_nop 1
	v_add_f32_dpp v40, v40, v40 row_mirror row_mask:0xf bank_mask:0xf bound_ctrl:1
	v_mul_f32_e32 v40, v114, v40
	v_fmac_f32_e32 v40, v46, v115
	v_add_f32_e32 v104, v47, v40
	v_pk_mul_f32 v[40:41], v[116:117], v[114:115] op_sel_hi:[1,0]
	ds_write_b32 v78, v104 offset:38400
	v_pk_fma_f32 v[42:43], v[88:89], v[46:47], v[40:41] op_sel_hi:[1,0,1]
	v_pk_mul_f32 v[40:41], v[118:119], v[114:115] op_sel_hi:[1,0]
	v_pk_mul_f32 v[88:89], v[112:113], v[114:115] op_sel_hi:[1,0]
	v_pk_fma_f32 v[44:45], v[90:91], v[46:47], v[40:41] op_sel_hi:[1,0,1]
	v_pk_mul_f32 v[40:41], v[120:121], v[114:115] op_sel_hi:[1,0]
	v_pk_fma_f32 v[40:41], v[96:97], v[46:47], v[40:41] op_sel_hi:[1,0,1]
	v_pk_fma_f32 v[46:47], v[98:99], v[46:47], v[88:89] op_sel_hi:[1,0,1]
	s_waitcnt lgkmcnt(1)
	v_pk_mul_f32 v[88:89], v[44:45], v[94:95]
	v_pk_mul_f32 v[90:91], v[46:47], v[102:103]
	v_pk_fma_f32 v[88:89], v[42:43], v[92:93], v[88:89]
	v_pk_fma_f32 v[90:91], v[40:41], v[100:101], v[90:91]
	s_waitcnt vmcnt(8)
	v_lshlrev_b32_e32 v94, 16, v21
	v_pk_add_f32 v[88:89], v[88:89], v[90:91]
	v_and_b32_e32 v95, 0xffff0000, v21
	v_add_f32_e32 v88, v88, v89
	v_lshlrev_b32_e32 v21, 16, v85
	v_lshlrev_b32_e32 v90, 16, v19
	v_add_f32_dpp v88, v88, v88 quad_perm:[1,0,3,2] row_mask:0xf bank_mask:0xf bound_ctrl:1
	v_and_b32_e32 v91, 0xffff0000, v19
	v_lshlrev_b32_e32 v19, 16, v84
	v_add_f32_dpp v88, v88, v88 quad_perm:[2,3,0,1] row_mask:0xf bank_mask:0xf bound_ctrl:1
	v_mul_f32_e32 v21, v50, v21
	v_and_b32_e32 v89, 0xffff0000, v18
	v_add_f32_dpp v88, v88, v88 row_half_mirror row_mask:0xf bank_mask:0xf bound_ctrl:1
	v_lshlrev_b32_e32 v92, 16, v20
	v_and_b32_e32 v93, 0xffff0000, v20
	v_add_f32_dpp v88, v88, v88 row_mirror row_mask:0xf bank_mask:0xf bound_ctrl:1
	s_waitcnt lgkmcnt(1)
	v_mul_f32_e32 v88, v38, v88
	v_fmac_f32_e32 v88, v8, v39
	v_add_f32_e32 v16, v16, v88
	ds_write_b32 v80, v16 offset:38400
	v_mul_f32_e32 v16, v49, v87
	v_fmac_f32_e32 v21, v16, v19
	v_mul_f32_e32 v16, v51, v86
	v_lshlrev_b32_e32 v19, 16, v83
	v_fmac_f32_e32 v21, v16, v19
	v_add_f32_e32 v16, v52, v21
	v_mul_f32_e32 v19, 0xbfb8aa3b, v16
	v_exp_f32_e32 v39, v19
	v_lshlrev_b32_e32 v88, 16, v18
	v_lshlrev_b32_e32 v18, 16, v12
	v_and_b32_e32 v19, 0xffff0000, v12
	v_add_f32_e32 v12, 1.0, v39
	v_rcp_f32_e32 v12, v12
	ds_write_b128 v58, v[92:95] offset:16
	ds_write_b128 v58, v[88:91]
	v_lshlrev_b32_e32 v20, 16, v13
	v_lshlrev_b32_e32 v90, 16, v15
	v_mul_f32_e32 v12, v16, v12
	v_lshlrev_b32_e32 v88, 16, v14
	v_and_b32_e32 v21, 0xffff0000, v13
	v_and_b32_e32 v91, 0xffff0000, v15
	v_and_b32_e32 v89, 0xffff0000, v14
	v_mul_f32_e32 v13, v36, v12
	v_mul_f32_e32 v12, v53, v12
	ds_write_b128 v58, v[88:91] offset:4112
	ds_write_b128 v58, v[18:21] offset:4096
	ds_write2st64_b32 v57, v13, v12 offset0:64 offset1:68
	s_and_saveexec_b64 s[4:5], vcc
	s_cbranch_execz .LBB0_543
	v_mov_b32_e32 v16, v37
	v_mov_b32_e32 v18, v157
	v_mov_b32_e32 v19, v157
	ds_write_b128 v72, v[16:19] offset:18432
	s_branch .LBB0_543
